# hand-written row-scaled GEMM epilogue (stores interleaved, write-back), lora bias loaded once per tile, final row pass stores without nt
# speedup vs baseline: 1.0484x; 1.0184x over previous
; __device__ __forceinline__ void rowpass_phase(KA a, int G, int which, const int tid, const int bid) {
;     ...
;     for (int t0 = gw; t0 < T_ALL; t0 += NR * NGW) {
;         int tt[NR]; float sc[NR]; f32x4 bvf[NR][4]; u32x2 bvh[NR][4], brw[NR][4];
; #pragma unroll
;         for (int q = 0; q < NR; ++q) {
;             const int t = t0 + q * NGW < T_ALL ? t0 + q * NGW : t0; tt[q] = t;
;             const bf16_t* BRp = which == 0 ? (const bf16_t*)(ws + WS_MO) + (size_t)t * DM : (which == 1 ? (const bf16_t*)(ws + WS_XO) + (size_t)t * DM
;                               : (t < FO_SPLIT ? (const bf16_t*)(ws + WS_KB) + (size_t)t * DM : (const bf16_t*)(ws + WS_FO_HI) + (size_t)(t - FO_SPLIT) * DM));
;             const u32x2* br = (const u32x2*)BRp + lane;
;             const u32x2* xb = (const u32x2*)(XBUF + (size_t)t * DM) + lane;
;             const f32x4* basef = (const f32x4*)xrow_ptr(a, t) + lane;
; #pragma unroll
;             for (int j = 0; j < 4; ++j) { if (which == 0) bvf[q][j] = __builtin_nontemporal_load(basef + 64 * j); else bvh[q][j] = __builtin_nontemporal_load(xb + 64 * j); brw[q][j] = __builtin_nontemporal_load(br + 64 * j); }
;             sc[q] = ssq[t];
;         }
; #pragma unroll
;         for (int q = 0; q < NR; ++q) {
;             if (q > 0 && tt[q] == t0) continue;
;             const int t = tt[q];
;             const float scl = __builtin_amdgcn_rsqf(sc[q] * (1.0f / DM) + 1e-6f);
;             u32x2* xb = (u32x2*)(XBUF + (size_t)t * DM) + lane;
;             f32x4* orow = (f32x4*)(AOUT + (size_t)t * DM) + lane;
;             f32x4 x[4]; float s = 0.f;
; #pragma unroll
;             for (int j = 0; j < 4; ++j) {
;                 f32x4 bv;
;                 if (which == 0) bv = bvf[q][j]; else { const u32x2 w1 = bvh[q][j]; bv = (f32x4){bflo(w1.x), bfhi(w1.x), bflo(w1.y), bfhi(w1.y)}; }
;                 const u32x2 w = brw[q][j];
;                 x[j].x = bv.x + bflo(w.x) * scl * gv[j].x; x[j].y = bv.y + bfhi(w.x) * scl * gv[j].y; x[j].z = bv.z + bflo(w.y) * scl * gv[j].z; x[j].w = bv.w + bfhi(w.y) * scl * gv[j].w;
;                 s += (x[j].x * x[j].x + x[j].y * x[j].y) + (x[j].z * x[j].z + x[j].w * x[j].w);
;             }
;             if (which == 2) {
; #pragma unroll
;                 for (int j = 0; j < 4; ++j) __builtin_nontemporal_store(x[j], orow + 64 * j);
.LBB0_216:
	s_andn2_saveexec_b64 s[12:13], s[12:13]
	v_ashrrev_i32_e32 v27, 31, v26
	v_lshlrev_b64 v[30:31], 11, v[26:27]
	v_lshl_add_u64 v[28:29], s[8:9], 0, v[30:31]
	s_or_b64 exec, exec, s[12:13]
	s_waitcnt vmcnt(4)
	v_lshlrev_b32_e32 v18, 3, v20
	v_lshl_add_u64 v[30:31], v[22:23], 0, v[30:31]
	v_lshl_add_u64 v[28:29], v[28:29], 0, v[18:19]
	global_load_dwordx2 v[76:77], v[30:31], off nt
	global_load_dwordx2 v[72:73], v[30:31], off offset:512 nt
	global_load_dwordx2 v[68:69], v[30:31], off offset:1024 nt
	global_load_dwordx2 v[60:61], v[30:31], off offset:1536 nt
	global_load_dwordx2 v[78:79], v[28:29], off nt
	global_load_dwordx2 v[74:75], v[28:29], off offset:512 nt
	global_load_dwordx2 v[70:71], v[28:29], off offset:1024 nt
	global_load_dwordx2 v[62:63], v[28:29], off offset:1536 nt
	v_lshl_add_u64 v[28:29], v[26:27], 2, s[4:5]
	global_load_dword v80, v[28:29], off
	v_add_u32_e32 v17, s14, v26
	v_cmp_gt_i32_e32 vcc, s79, v17
	s_nop 1
	v_cndmask_b32_e32 v30, v26, v17, vcc
	v_cmp_lt_i32_e32 vcc, s84, v30
	s_and_saveexec_b64 s[12:13], vcc
	s_xor_b64 s[12:13], exec, s[12:13]
	v_add_u32_e32 v28, 0xfffff000, v30
	v_mov_b32_e32 v29, v19
	v_lshlrev_b64 v[28:29], 11, v[28:29]
	v_mov_b32_e32 v31, v19
	v_lshl_add_u64 v[28:29], s[6:7], 0, v[28:29]
	v_lshlrev_b64 v[32:33], 11, v[30:31]
	s_andn2_saveexec_b64 s[12:13], s[12:13]
	v_ashrrev_i32_e32 v31, 31, v30
	v_lshlrev_b64 v[32:33], 11, v[30:31]
	v_lshl_add_u64 v[28:29], s[8:9], 0, v[32:33]
	s_or_b64 exec, exec, s[12:13]
	v_lshl_add_u64 v[32:33], v[22:23], 0, v[32:33]
	v_lshl_add_u64 v[28:29], v[28:29], 0, v[18:19]
	global_load_dwordx2 v[64:65], v[32:33], off nt
	global_load_dwordx2 v[56:57], v[32:33], off offset:512 nt
	global_load_dwordx2 v[52:53], v[32:33], off offset:1024 nt
	global_load_dwordx2 v[44:45], v[32:33], off offset:1536 nt
	global_load_dwordx2 v[66:67], v[28:29], off nt
	global_load_dwordx2 v[58:59], v[28:29], off offset:512 nt
	global_load_dwordx2 v[54:55], v[28:29], off offset:1024 nt
	global_load_dwordx2 v[46:47], v[28:29], off offset:1536 nt
	v_lshl_add_u64 v[28:29], v[30:31], 2, s[4:5]
	global_load_dword v21, v[28:29], off
	v_add_u32_e32 v28, s15, v26
	v_cmp_gt_i32_e32 vcc, s79, v28
	s_nop 1
	v_cndmask_b32_e32 v28, v26, v28, vcc
	v_cmp_lt_i32_e32 vcc, s84, v28
	s_and_saveexec_b64 s[12:13], vcc
	s_xor_b64 s[12:13], exec, s[12:13]
	v_add_u32_e32 v32, 0xfffff000, v28
	v_mov_b32_e32 v33, v19
	v_lshlrev_b64 v[32:33], 11, v[32:33]
	v_mov_b32_e32 v29, v19
	v_lshl_add_u64 v[32:33], s[6:7], 0, v[32:33]
	v_lshlrev_b64 v[34:35], 11, v[28:29]
	s_andn2_saveexec_b64 s[12:13], s[12:13]
	v_ashrrev_i32_e32 v29, 31, v28
	v_lshlrev_b64 v[34:35], 11, v[28:29]
	v_lshl_add_u64 v[32:33], s[8:9], 0, v[34:35]
	s_or_b64 exec, exec, s[12:13]
	v_lshl_add_u64 v[82:83], v[32:33], 0, v[18:19]
	v_lshl_add_u64 v[32:33], v[22:23], 0, v[34:35]
	global_load_dwordx2 v[48:49], v[32:33], off nt
	global_load_dwordx2 v[40:41], v[32:33], off offset:512 nt
	global_load_dwordx2 v[36:37], v[32:33], off offset:1024 nt
	s_nop 0
	global_load_dwordx2 v[32:33], v[32:33], off offset:1536 nt
	s_nop 0
	global_load_dwordx2 v[50:51], v[82:83], off nt
	global_load_dwordx2 v[42:43], v[82:83], off offset:512 nt
	global_load_dwordx2 v[38:39], v[82:83], off offset:1024 nt
	global_load_dwordx2 v[34:35], v[82:83], off offset:1536 nt
	v_lshl_add_u64 v[82:83], v[28:29], 2, s[4:5]
	global_load_dword v18, v[82:83], off
	s_waitcnt vmcnt(18)
	v_fmamk_f32 v80, v80, 0x3a800000, v163
	v_rsq_f32_e32 v84, v80
	v_lshlrev_b32_e32 v82, 16, v78
	v_and_b32_e32 v83, 0xffff0000, v78
	v_lshlrev_b32_e32 v78, 16, v79
	v_and_b32_e32 v79, 0xffff0000, v79
	v_lshlrev_b32_e32 v80, 16, v76
	v_and_b32_e32 v81, 0xffff0000, v76
	v_pk_mul_f32 v[82:83], v[84:85], v[82:83] op_sel_hi:[0,1]
	v_lshlrev_b32_e32 v76, 16, v77
	v_and_b32_e32 v77, 0xffff0000, v77
	v_pk_mul_f32 v[78:79], v[84:85], v[78:79] op_sel_hi:[0,1]
	v_pk_fma_f32 v[80:81], v[12:13], v[82:83], v[80:81]
	v_pk_fma_f32 v[82:83], v[14:15], v[78:79], v[76:77]
	v_lshlrev_b32_e32 v78, 16, v74
	v_and_b32_e32 v79, 0xffff0000, v74
	v_lshlrev_b32_e32 v74, 16, v75
	v_and_b32_e32 v75, 0xffff0000, v75
	v_lshlrev_b32_e32 v76, 16, v72
	v_and_b32_e32 v77, 0xffff0000, v72
	v_pk_mul_f32 v[78:79], v[84:85], v[78:79] op_sel_hi:[0,1]
	v_lshlrev_b32_e32 v72, 16, v73
	v_and_b32_e32 v73, 0xffff0000, v73
	v_pk_mul_f32 v[74:75], v[84:85], v[74:75] op_sel_hi:[0,1]
	v_pk_fma_f32 v[76:77], v[8:9], v[78:79], v[76:77]
	v_pk_fma_f32 v[78:79], v[10:11], v[74:75], v[72:73]
	v_lshlrev_b32_e32 v74, 16, v70
	v_and_b32_e32 v75, 0xffff0000, v70
	v_lshlrev_b32_e32 v70, 16, v71
	v_and_b32_e32 v71, 0xffff0000, v71
	v_lshlrev_b32_e32 v72, 16, v68
	v_and_b32_e32 v73, 0xffff0000, v68
	v_pk_mul_f32 v[74:75], v[84:85], v[74:75] op_sel_hi:[0,1]
	v_lshlrev_b32_e32 v68, 16, v69
	v_and_b32_e32 v69, 0xffff0000, v69
	v_pk_mul_f32 v[70:71], v[84:85], v[70:71] op_sel_hi:[0,1]
	v_pk_fma_f32 v[72:73], v[4:5], v[74:75], v[72:73]
	v_pk_fma_f32 v[74:75], v[6:7], v[70:71], v[68:69]
	v_lshlrev_b32_e32 v70, 16, v62
	v_and_b32_e32 v71, 0xffff0000, v62
	v_lshlrev_b32_e32 v62, 16, v63
	v_and_b32_e32 v63, 0xffff0000, v63
	v_lshlrev_b32_e32 v68, 16, v60
	v_and_b32_e32 v69, 0xffff0000, v60
	v_pk_mul_f32 v[70:71], v[84:85], v[70:71] op_sel_hi:[0,1]
	v_lshlrev_b32_e32 v60, 16, v61
	v_and_b32_e32 v61, 0xffff0000, v61
	v_pk_mul_f32 v[62:63], v[84:85], v[62:63] op_sel_hi:[0,1]
	v_pk_fma_f32 v[68:69], v[0:1], v[70:71], v[68:69]
	v_pk_fma_f32 v[70:71], v[2:3], v[62:63], v[60:61]
	v_lshlrev_b64 v[60:61], 12, v[26:27]
	v_lshl_add_u64 v[60:61], v[24:25], 0, v[60:61]
	v_cmp_ne_u32_e32 vcc, v26, v30
	global_store_dwordx4 v[60:61], v[80:83], off
	global_store_dwordx4 v[60:61], v[76:79], off offset:1024
	global_store_dwordx4 v[60:61], v[72:75], off offset:2048
	global_store_dwordx4 v[60:61], v[68:71], off offset:3072
	s_and_saveexec_b64 s[12:13], vcc
	s_cbranch_execz .LBB0_228
; __device__ __forceinline__ void rowpass_phase(KA a, int G, int which, const int tid, const int bid) {
;     ...
;         for (int q = 0; q < NR; ++q) {
;             if (q > 0 && tt[q] == t0) continue;
;             const int t = tt[q];
;             const float scl = __builtin_amdgcn_rsqf(sc[q] * (1.0f / DM) + 1e-6f);
;             u32x2* xb = (u32x2*)(XBUF + (size_t)t * DM) + lane;
;             f32x4* orow = (f32x4*)(AOUT + (size_t)t * DM) + lane;
;             f32x4 x[4]; float s = 0.f;
; #pragma unroll
;             for (int j = 0; j < 4; ++j) {
;                 f32x4 bv;
;                 if (which == 0) bv = bvf[q][j]; else { const u32x2 w1 = bvh[q][j]; bv = (f32x4){bflo(w1.x), bfhi(w1.x), bflo(w1.y), bfhi(w1.y)}; }
;                 const u32x2 w = brw[q][j];
;                 x[j].x = bv.x + bflo(w.x) * scl * gv[j].x; x[j].y = bv.y + bfhi(w.x) * scl * gv[j].y; x[j].z = bv.z + bflo(w.y) * scl * gv[j].z; x[j].w = bv.w + bfhi(w.y) * scl * gv[j].w;
;                 s += (x[j].x * x[j].x + x[j].y * x[j].y) + (x[j].z * x[j].z + x[j].w * x[j].w);
;             }
;             if (which == 2) {
; #pragma unroll
;                 for (int j = 0; j < 4; ++j) __builtin_nontemporal_store(x[j], orow + 64 * j);
	s_waitcnt vmcnt(13)
	v_fmamk_f32 v21, v21, 0x3a800000, v163
	v_rsq_f32_e32 v68, v21
	v_lshlrev_b32_e32 v62, 16, v66
	v_and_b32_e32 v63, 0xffff0000, v66
	v_lshlrev_b32_e32 v60, 16, v64
	v_and_b32_e32 v61, 0xffff0000, v64
	v_pk_mul_f32 v[62:63], v[68:69], v[62:63] op_sel_hi:[0,1]
	v_pk_fma_f32 v[60:61], v[12:13], v[62:63], v[60:61]
	v_lshlrev_b32_e32 v62, 16, v65
	v_and_b32_e32 v63, 0xffff0000, v65
	v_lshlrev_b32_e32 v64, 16, v67
	v_and_b32_e32 v65, 0xffff0000, v67
	v_pk_mul_f32 v[64:65], v[68:69], v[64:65] op_sel_hi:[0,1]
	v_lshlrev_b32_e32 v66, 16, v58
	v_and_b32_e32 v67, 0xffff0000, v58
	v_lshlrev_b32_e32 v58, 16, v59
	v_and_b32_e32 v59, 0xffff0000, v59
	v_pk_fma_f32 v[62:63], v[14:15], v[64:65], v[62:63]
	v_lshlrev_b32_e32 v64, 16, v56
	v_and_b32_e32 v65, 0xffff0000, v56
	v_pk_mul_f32 v[66:67], v[68:69], v[66:67] op_sel_hi:[0,1]
	v_lshlrev_b32_e32 v56, 16, v57
	v_and_b32_e32 v57, 0xffff0000, v57
	v_pk_mul_f32 v[58:59], v[68:69], v[58:59] op_sel_hi:[0,1]
	v_pk_fma_f32 v[64:65], v[8:9], v[66:67], v[64:65]
	v_pk_fma_f32 v[66:67], v[10:11], v[58:59], v[56:57]
	v_lshlrev_b32_e32 v58, 16, v54
	v_and_b32_e32 v59, 0xffff0000, v54
	v_lshlrev_b32_e32 v54, 16, v55
	v_and_b32_e32 v55, 0xffff0000, v55
	v_lshlrev_b32_e32 v56, 16, v52
	v_and_b32_e32 v57, 0xffff0000, v52
	v_pk_mul_f32 v[58:59], v[68:69], v[58:59] op_sel_hi:[0,1]
	v_lshlrev_b32_e32 v52, 16, v53
	v_and_b32_e32 v53, 0xffff0000, v53
	v_pk_mul_f32 v[54:55], v[68:69], v[54:55] op_sel_hi:[0,1]
	v_pk_fma_f32 v[56:57], v[4:5], v[58:59], v[56:57]
	v_pk_fma_f32 v[58:59], v[6:7], v[54:55], v[52:53]
	v_lshlrev_b32_e32 v54, 16, v46
	v_and_b32_e32 v55, 0xffff0000, v46
	v_lshlrev_b32_e32 v46, 16, v47
	v_and_b32_e32 v47, 0xffff0000, v47
	v_lshlrev_b64 v[30:31], 12, v[30:31]
	v_lshlrev_b32_e32 v52, 16, v44
	v_and_b32_e32 v53, 0xffff0000, v44
	v_pk_mul_f32 v[54:55], v[68:69], v[54:55] op_sel_hi:[0,1]
	v_lshlrev_b32_e32 v44, 16, v45
	v_and_b32_e32 v45, 0xffff0000, v45
	v_pk_mul_f32 v[46:47], v[68:69], v[46:47] op_sel_hi:[0,1]
	v_lshl_add_u64 v[30:31], v[24:25], 0, v[30:31]
	v_pk_fma_f32 v[52:53], v[0:1], v[54:55], v[52:53]
	v_pk_fma_f32 v[54:55], v[2:3], v[46:47], v[44:45]
	global_store_dwordx4 v[30:31], v[60:63], off
	global_store_dwordx4 v[30:31], v[64:67], off offset:1024
	global_store_dwordx4 v[30:31], v[56:59], off offset:2048
	global_store_dwordx4 v[30:31], v[52:55], off offset:3072
.LBB0_228:
	s_or_b64 exec, exec, s[12:13]
	v_cmp_ne_u32_e32 vcc, v26, v28
	s_and_saveexec_b64 s[12:13], vcc
	s_cbranch_execz .LBB0_213
	s_waitcnt vmcnt(4)
	v_fmamk_f32 v18, v18, 0x3a800000, v163
	v_rsq_f32_e32 v18, v18
	v_lshlrev_b32_e32 v30, 16, v50
	v_and_b32_e32 v31, 0xffff0000, v50
	v_lshlrev_b32_e32 v26, 16, v48
	v_and_b32_e32 v27, 0xffff0000, v48
	v_pk_mul_f32 v[30:31], v[18:19], v[30:31] op_sel_hi:[0,1]
	v_pk_fma_f32 v[44:45], v[12:13], v[30:31], v[26:27]
	v_lshlrev_b32_e32 v30, 16, v51
	v_and_b32_e32 v31, 0xffff0000, v51
	v_lshlrev_b32_e32 v26, 16, v49
	v_and_b32_e32 v27, 0xffff0000, v49
	v_pk_mul_f32 v[30:31], v[18:19], v[30:31] op_sel_hi:[0,1]
	v_pk_fma_f32 v[46:47], v[14:15], v[30:31], v[26:27]
	v_lshlrev_b32_e32 v30, 16, v42
	v_and_b32_e32 v31, 0xffff0000, v42
	v_lshlrev_b32_e32 v26, 16, v40
	v_and_b32_e32 v27, 0xffff0000, v40
	v_pk_mul_f32 v[30:31], v[18:19], v[30:31] op_sel_hi:[0,1]
	v_pk_fma_f32 v[48:49], v[8:9], v[30:31], v[26:27]
	v_lshlrev_b32_e32 v30, 16, v43
	v_and_b32_e32 v31, 0xffff0000, v43
	v_lshlrev_b32_e32 v26, 16, v41
	v_and_b32_e32 v27, 0xffff0000, v41
	v_pk_mul_f32 v[30:31], v[18:19], v[30:31] op_sel_hi:[0,1]
	v_pk_fma_f32 v[50:51], v[10:11], v[30:31], v[26:27]
	v_lshlrev_b32_e32 v30, 16, v38
	v_and_b32_e32 v31, 0xffff0000, v38
	v_lshlrev_b32_e32 v26, 16, v36
	v_and_b32_e32 v27, 0xffff0000, v36
	v_pk_mul_f32 v[30:31], v[18:19], v[30:31] op_sel_hi:[0,1]
	v_pk_fma_f32 v[40:41], v[4:5], v[30:31], v[26:27]
	v_lshlrev_b32_e32 v30, 16, v39
	v_and_b32_e32 v31, 0xffff0000, v39
	v_lshlrev_b32_e32 v26, 16, v37
	v_and_b32_e32 v27, 0xffff0000, v37
	v_pk_mul_f32 v[30:31], v[18:19], v[30:31] op_sel_hi:[0,1]
	v_pk_fma_f32 v[42:43], v[6:7], v[30:31], v[26:27]
	v_lshlrev_b32_e32 v30, 16, v34
	v_and_b32_e32 v31, 0xffff0000, v34
	v_lshlrev_b32_e32 v26, 16, v32
	v_and_b32_e32 v27, 0xffff0000, v32
	v_pk_mul_f32 v[30:31], v[18:19], v[30:31] op_sel_hi:[0,1]
	v_pk_fma_f32 v[30:31], v[0:1], v[30:31], v[26:27]
	v_lshlrev_b32_e32 v26, 16, v33
	v_and_b32_e32 v27, 0xffff0000, v33
	v_lshlrev_b32_e32 v32, 16, v35
	v_and_b32_e32 v33, 0xffff0000, v35
	v_pk_mul_f32 v[32:33], v[18:19], v[32:33] op_sel_hi:[0,1]
	v_pk_fma_f32 v[32:33], v[2:3], v[32:33], v[26:27]
	v_lshlrev_b64 v[26:27], 12, v[28:29]
	v_lshl_add_u64 v[26:27], v[24:25], 0, v[26:27]
	global_store_dwordx4 v[26:27], v[44:47], off
	global_store_dwordx4 v[26:27], v[48:51], off offset:1024
	global_store_dwordx4 v[26:27], v[40:43], off offset:2048
	global_store_dwordx4 v[26:27], v[30:33], off offset:3072
	s_branch .LBB0_213

; __device__ __forceinline__ unsigned pk2(float lo, float hi) { const f32x2 v = {lo, hi}; return __builtin_bit_cast(unsigned, __builtin_convertvector(v, bf16x2_t)); }
; __device__ __forceinline__ float sigmoidf_(float z) { return __builtin_amdgcn_rcpf(1.0f + __expf(-z)); }
;     __device__ __forceinline__ void operator()(const f32x4 (&acc)[2][2][4][2], const Unit& u, int wr, int wc, int fr, int fq) const {
;     ...
;                 const float rsc = P.rowscale ? P.scal * P.rowscale[row] : P.scal;
;                 float ss = 0.f;
; #pragma unroll
;                 for (int bj = 0; bj < 2; ++bj) {
;                     const int col = colbase + bj * HALF;
;                     f32x4 v0 = acc[ai][bj][m][0] * rsc, v1 = acc[ai][bj][m][1] * rsc;
;                     if (P.colscale) { const f32x4 c0 = *(const f32x4*)(P.colscale + col), c1 = *(const f32x4*)(P.colscale + col + 4); v0 = v0 * c0; v1 = v1 * c1; }
;                     if (P.act == 1) {
; #pragma unroll
;                         for (int j = 0; j < 4; ++j) { const float a0 = v0[j] > 0.f ? v0[j] : 0.f, a1 = v1[j] > 0.f ? v1[j] : 0.f; v0[j] = a0 * a0; v1[j] = a1 * a1; }
;                     }
;                     bf16_t* dst = (row < P.split ? P.Olo : P.O) + (size_t)row * P.ldc + col;
;                     if (P.act == 2) {
;                         if (grp < 4) {
;                             const int bc = col - grp * 512;
;                             const f32x4 c0 = *(const f32x4*)(bias + bc), c1 = *(const f32x4*)(bias + bc + 4);
;                             const float mul = grp < 2 ? -0.60653066f : 1.0f;
; #pragma unroll
;                             for (int j = 0; j < 4; ++j) { v0[j] = mul * sigmoidf_(v0[j] + c0[j]); v1[j] = mul * sigmoidf_(v1[j] + c1[j]); }
;                         } else dst = P.O2 + (size_t)row * 512 + (col - 2048);
;                     }
;                     if (P.ssq) ss += (v0[0] * v0[0] + v0[1] * v0[1]) + (v0[2] * v0[2] + v0[3] * v0[3]) + (v1[0] * v1[0] + v1[1] * v1[1]) + (v1[2] * v1[2] + v1[3] * v1[3]);
;                     if (col < P.ncols) { u32x4 w; w.x = pk2(v0[0], v0[1]); w.y = pk2(v0[2], v0[3]); w.z = pk2(v1[0], v1[1]); w.w = pk2(v1[2], v1[3]);
;                         if (P.ldc >= 3504) __builtin_nontemporal_store(w, (u32x4*)dst); else *(u32x4*)dst = w; }
.LBB0_515:
	s_waitcnt lgkmcnt(0)
	s_cmp_eq_u64 s[16:17], 0
	s_cbranch_scc1 .Lfe_generic
	s_cmp_lg_u64 s[18:19], 0
	s_cbranch_scc1 .Lfe_generic
	s_cmp_lg_u64 s[20:21], 0
	s_cbranch_scc1 .Lfe_generic
	s_cmp_lg_u64 s[54:55], 0
	s_cbranch_scc1 .Lfe_generic
	s_cmp_lg_u32 s45, 0
	s_cbranch_scc0 .Lfe_fast

; __device__ __forceinline__ float sigmoidf_(float z) { return __builtin_amdgcn_rcpf(1.0f + __expf(-z)); }
;     __device__ __forceinline__ void operator()(const f32x4 (&acc)[2][2][4][2], const Unit& u, int wr, int wc, int fr, int fq) const {
;     ...
;                     if (P.act == 2) {
;                         if (grp < 4) {
;                             const int bc = col - grp * 512;
;                             const f32x4 c0 = *(const f32x4*)(bias + bc), c1 = *(const f32x4*)(bias + bc + 4);
;                             const float mul = grp < 2 ? -0.60653066f : 1.0f;
; #pragma unroll
;                             for (int j = 0; j < 4; ++j) { v0[j] = mul * sigmoidf_(v0[j] + c0[j]); v1[j] = mul * sigmoidf_(v1[j] + c1[j]); }
;                         } else dst = P.O2 + (size_t)row * 512 + (col - 2048);
.LBB0_533:
	s_andn2_b64 vcc, exec, s[22:23]
	s_cbranch_vccnz .LBB0_733
	s_ashr_i32 s22, s7, 31
	v_mov_b32_e32 v125, s22
	v_subrev_co_u32_e32 v154, vcc, s7, v146
	s_nop 1
	v_subb_co_u32_e32 v155, vcc, v147, v125, vcc
	v_lshl_add_u64 v[154:155], v[154:155], 2, s[62:63]
	v_mov_b32_e32 v194, v218
	v_mov_b32_e32 v195, v219
	v_mov_b32_e32 v196, v220
	v_mov_b32_e32 v197, v221
	v_mov_b32_e32 v198, v222
	v_mov_b32_e32 v199, v223
	v_mov_b32_e32 v200, v224
	v_mov_b32_e32 v201, v225
	v_add_f32_e32 v120, v120, v194
	v_add_f32_e32 v125, v152, v198
	v_add_f32_e32 v121, v121, v195
	v_add_f32_e32 v152, v153, v199
	v_add_f32_e32 v122, v122, v196
	v_add_f32_e32 v118, v118, v200
	v_add_f32_e32 v123, v123, v197
	v_add_f32_e32 v119, v119, v201
	v_mul_f32_e32 v120, 0xbfb8aa3b, v120
	v_mul_f32_e32 v125, 0xbfb8aa3b, v125
	v_mul_f32_e32 v121, 0xbfb8aa3b, v121
	v_mul_f32_e32 v152, 0xbfb8aa3b, v152
	v_mul_f32_e32 v122, 0xbfb8aa3b, v122
	v_mul_f32_e32 v118, 0xbfb8aa3b, v118
	v_mul_f32_e32 v123, 0xbfb8aa3b, v123
	v_mul_f32_e32 v119, 0xbfb8aa3b, v119
	v_exp_f32_e32 v120, v120
	v_exp_f32_e32 v125, v125
	v_exp_f32_e32 v121, v121
	v_exp_f32_e32 v152, v152
	v_exp_f32_e32 v122, v122
	v_exp_f32_e32 v118, v118
	v_exp_f32_e32 v123, v123
	v_exp_f32_e32 v119, v119
	v_add_f32_e32 v120, 1.0, v120
	v_add_f32_e32 v125, 1.0, v125
	v_add_f32_e32 v121, 1.0, v121
	v_add_f32_e32 v153, 1.0, v152
	v_add_f32_e32 v122, 1.0, v122
	v_add_f32_e32 v154, 1.0, v118
	v_add_f32_e32 v123, 1.0, v123
	v_add_f32_e32 v155, 1.0, v119
	v_rcp_f32_e32 v118, v120
	v_rcp_f32_e32 v152, v125
	v_rcp_f32_e32 v119, v121
	v_rcp_f32_e32 v120, v122
	v_rcp_f32_e32 v121, v123
	v_rcp_f32_e32 v154, v154
	v_rcp_f32_e32 v155, v155
	v_rcp_f32_e32 v153, v153
	v_pk_mul_f32 v[122:123], v[124:125], v[120:121] op_sel_hi:[0,1]
	v_pk_mul_f32 v[120:121], v[124:125], v[118:119] op_sel_hi:[0,1]
	v_pk_mul_f32 v[118:119], v[124:125], v[154:155] op_sel_hi:[0,1]
	v_pk_mul_f32 v[152:153], v[124:125], v[152:153] op_sel_hi:[0,1]

; __device__ __forceinline__ unsigned pk2(float lo, float hi) { const f32x2 v = {lo, hi}; return __builtin_bit_cast(unsigned, __builtin_convertvector(v, bf16x2_t)); }
;     __device__ __forceinline__ void operator()(const f32x4 (&acc)[2][2][4][2], const Unit& u, int wr, int wc, int fr, int fq) const {
;     ...
;             for (int m = 0; m < 4; ++m) {
;                 const int row = u.pm * BM + ai * HALF + wr * 64 + m * 16 + fr;
;                 const float rsc = P.rowscale ? P.scal * P.rowscale[row] : P.scal;
;                 float ss = 0.f;
; #pragma unroll
;                 for (int bj = 0; bj < 2; ++bj) {
;                     const int col = colbase + bj * HALF;
;                     f32x4 v0 = acc[ai][bj][m][0] * rsc, v1 = acc[ai][bj][m][1] * rsc;
;                     if (P.colscale) { const f32x4 c0 = *(const f32x4*)(P.colscale + col), c1 = *(const f32x4*)(P.colscale + col + 4); v0 = v0 * c0; v1 = v1 * c1; }
;                     if (P.act == 1) {
; #pragma unroll
;                         for (int j = 0; j < 4; ++j) { const float a0 = v0[j] > 0.f ? v0[j] : 0.f, a1 = v1[j] > 0.f ? v1[j] : 0.f; v0[j] = a0 * a0; v1[j] = a1 * a1; }
;                     }
;                     bf16_t* dst = (row < P.split ? P.Olo : P.O) + (size_t)row * P.ldc + col;
;                     if (P.act == 2) {
;                         if (grp < 4) {
;                             const int bc = col - grp * 512;
;                             const f32x4 c0 = *(const f32x4*)(bias + bc), c1 = *(const f32x4*)(bias + bc + 4);
;                             const float mul = grp < 2 ? -0.60653066f : 1.0f;
; #pragma unroll
;                             for (int j = 0; j < 4; ++j) { v0[j] = mul * sigmoidf_(v0[j] + c0[j]); v1[j] = mul * sigmoidf_(v1[j] + c1[j]); }
;                         } else dst = P.O2 + (size_t)row * 512 + (col - 2048);
;                     }
;                     if (P.ssq) ss += (v0[0] * v0[0] + v0[1] * v0[1]) + (v0[2] * v0[2] + v0[3] * v0[3]) + (v1[0] * v1[0] + v1[1] * v1[1]) + (v1[2] * v1[2] + v1[3] * v1[3]);
;                     if (col < P.ncols) { u32x4 w; w.x = pk2(v0[0], v0[1]); w.y = pk2(v0[2], v0[3]); w.z = pk2(v1[0], v1[1]); w.w = pk2(v1[2], v1[3]);
;                         if (P.ldc >= 3504) __builtin_nontemporal_store(w, (u32x4*)dst); else *(u32x4*)dst = w; }
.Lfe_fast:
	v_lshl_add_u32 v144, s70, 8, v190
	v_ashrrev_i32_e32 v145, 31, v144
	v_lshl_add_u64 v[148:149], v[144:145], 2, s[16:17]
	global_load_dword v202, v[148:149], off
	global_load_dword v203, v[148:149], off offset:64
	global_load_dword v204, v[148:149], off offset:128
	global_load_dword v205, v[148:149], off offset:192
	global_load_dword v206, v[148:149], off offset:512
	global_load_dword v207, v[148:149], off offset:576
	global_load_dword v208, v[148:149], off offset:640
	global_load_dword v209, v[148:149], off offset:704
	v_lshl_or_b32 v146, s7, 8, v192
	v_or_b32_e32 v147, 0x80, v146
	v_cmp_gt_i32_e64 s[18:19], s29, v146
	v_cmp_gt_i32_e64 s[20:21], s29, v147
	v_mul_lo_u32 v150, v144, s58
	v_add_lshl_u32 v150, v150, v146, 1
	s_lshl_b32 s12, s58, 5
	s_mul_i32 s13, s58, 0xa0
	v_add_u32_e32 v151, s12, v150
	v_add_u32_e32 v152, s12, v151
	v_add_u32_e32 v153, s12, v152
	v_add_u32_e32 v154, s13, v153
	v_add_u32_e32 v155, s12, v154
	v_add_u32_e32 v156, s12, v155
	v_add_u32_e32 v157, s12, v156
	s_mov_b64 s[14:15], exec
	s_and_b64 s[18:19], s[14:15], s[18:19]
	s_and_b64 s[20:21], s[14:15], s[20:21]
	s_and_b64 vcc, exec, s[26:27]
	s_waitcnt vmcnt(0)
	v_mul_f32_e32 v158, s44, v202
	v_pk_mul_f32 v[124:125], v[124:125], v[158:159] op_sel_hi:[1,0]
	v_pk_mul_f32 v[126:127], v[126:127], v[158:159] op_sel_hi:[1,0]
	v_pk_mul_f32 v[128:129], v[128:129], v[158:159] op_sel_hi:[1,0]
	v_pk_mul_f32 v[130:131], v[130:131], v[158:159] op_sel_hi:[1,0]
	v_pk_mul_f32 v[116:117], v[116:117], v[158:159] op_sel_hi:[1,0]
	v_pk_mul_f32 v[118:119], v[118:119], v[158:159] op_sel_hi:[1,0]
	v_pk_mul_f32 v[120:121], v[120:121], v[158:159] op_sel_hi:[1,0]
	v_pk_mul_f32 v[122:123], v[122:123], v[158:159] op_sel_hi:[1,0]
	s_cbranch_vccz .Lfe_nr0
	v_max_f32_e32 v124, 0, v124
	v_max_f32_e32 v125, 0, v125
	v_max_f32_e32 v126, 0, v126
	v_max_f32_e32 v127, 0, v127
	v_max_f32_e32 v128, 0, v128
	v_max_f32_e32 v129, 0, v129
	v_max_f32_e32 v130, 0, v130
	v_max_f32_e32 v131, 0, v131
	v_max_f32_e32 v116, 0, v116
	v_max_f32_e32 v117, 0, v117
	v_max_f32_e32 v118, 0, v118
	v_max_f32_e32 v119, 0, v119
	v_max_f32_e32 v120, 0, v120
	v_max_f32_e32 v121, 0, v121
	v_max_f32_e32 v122, 0, v122
	v_max_f32_e32 v123, 0, v123
	v_pk_mul_f32 v[124:125], v[124:125], v[124:125]
	v_pk_mul_f32 v[126:127], v[126:127], v[126:127]
	v_pk_mul_f32 v[128:129], v[128:129], v[128:129]
	v_pk_mul_f32 v[130:131], v[130:131], v[130:131]
	v_pk_mul_f32 v[116:117], v[116:117], v[116:117]
	v_pk_mul_f32 v[118:119], v[118:119], v[118:119]
	v_pk_mul_f32 v[120:121], v[120:121], v[120:121]
	v_pk_mul_f32 v[122:123], v[122:123], v[122:123]
.Lfe_nr0:
	v_cvt_pk_bf16_f32 v128, v128, v129
	v_cvt_pk_bf16_f32 v129, v130, v131
	v_cvt_pk_bf16_f32 v130, v124, v125
	v_cvt_pk_bf16_f32 v131, v126, v127
	v_cvt_pk_bf16_f32 v120, v120, v121
	v_cvt_pk_bf16_f32 v121, v122, v123
	v_cvt_pk_bf16_f32 v122, v116, v117
	v_cvt_pk_bf16_f32 v123, v118, v119
	s_mov_b64 exec, s[18:19]
	global_store_dwordx4 v150, v[128:131], s[56:57]
	s_mov_b64 exec, s[20:21]
	global_store_dwordx4 v150, v[120:123], s[56:57] offset:256
	s_mov_b64 exec, s[14:15]
	v_mul_f32_e32 v158, s44, v203
	v_pk_mul_f32 v[108:109], v[108:109], v[158:159] op_sel_hi:[1,0]
	v_pk_mul_f32 v[110:111], v[110:111], v[158:159] op_sel_hi:[1,0]
	v_pk_mul_f32 v[112:113], v[112:113], v[158:159] op_sel_hi:[1,0]
	v_pk_mul_f32 v[114:115], v[114:115], v[158:159] op_sel_hi:[1,0]
	v_pk_mul_f32 v[100:101], v[100:101], v[158:159] op_sel_hi:[1,0]
	v_pk_mul_f32 v[102:103], v[102:103], v[158:159] op_sel_hi:[1,0]
	v_pk_mul_f32 v[104:105], v[104:105], v[158:159] op_sel_hi:[1,0]
	v_pk_mul_f32 v[106:107], v[106:107], v[158:159] op_sel_hi:[1,0]
	s_cbranch_vccz .Lfe_nr1
	v_max_f32_e32 v108, 0, v108
	v_max_f32_e32 v109, 0, v109
	v_max_f32_e32 v110, 0, v110
	v_max_f32_e32 v111, 0, v111
	v_max_f32_e32 v112, 0, v112
	v_max_f32_e32 v113, 0, v113
	v_max_f32_e32 v114, 0, v114
	v_max_f32_e32 v115, 0, v115
	v_max_f32_e32 v100, 0, v100
	v_max_f32_e32 v101, 0, v101
	v_max_f32_e32 v102, 0, v102
	v_max_f32_e32 v103, 0, v103
	v_max_f32_e32 v104, 0, v104
	v_max_f32_e32 v105, 0, v105
	v_max_f32_e32 v106, 0, v106
	v_max_f32_e32 v107, 0, v107
	v_pk_mul_f32 v[108:109], v[108:109], v[108:109]
	v_pk_mul_f32 v[110:111], v[110:111], v[110:111]
	v_pk_mul_f32 v[112:113], v[112:113], v[112:113]
	v_pk_mul_f32 v[114:115], v[114:115], v[114:115]
	v_pk_mul_f32 v[100:101], v[100:101], v[100:101]
	v_pk_mul_f32 v[102:103], v[102:103], v[102:103]
	v_pk_mul_f32 v[104:105], v[104:105], v[104:105]
	v_pk_mul_f32 v[106:107], v[106:107], v[106:107]
.Lfe_nr1:
	v_cvt_pk_bf16_f32 v112, v112, v113
	v_cvt_pk_bf16_f32 v113, v114, v115
	v_cvt_pk_bf16_f32 v114, v108, v109
	v_cvt_pk_bf16_f32 v115, v110, v111
	v_cvt_pk_bf16_f32 v104, v104, v105
	v_cvt_pk_bf16_f32 v105, v106, v107
	v_cvt_pk_bf16_f32 v106, v100, v101
	v_cvt_pk_bf16_f32 v107, v102, v103
	s_mov_b64 exec, s[18:19]
	global_store_dwordx4 v151, v[112:115], s[56:57]
	s_mov_b64 exec, s[20:21]
	global_store_dwordx4 v151, v[104:107], s[56:57] offset:256
	s_mov_b64 exec, s[14:15]
	v_mul_f32_e32 v158, s44, v204
	v_pk_mul_f32 v[92:93], v[92:93], v[158:159] op_sel_hi:[1,0]
	v_pk_mul_f32 v[94:95], v[94:95], v[158:159] op_sel_hi:[1,0]
	v_pk_mul_f32 v[96:97], v[96:97], v[158:159] op_sel_hi:[1,0]
	v_pk_mul_f32 v[98:99], v[98:99], v[158:159] op_sel_hi:[1,0]
	v_pk_mul_f32 v[84:85], v[84:85], v[158:159] op_sel_hi:[1,0]
	v_pk_mul_f32 v[86:87], v[86:87], v[158:159] op_sel_hi:[1,0]
	v_pk_mul_f32 v[88:89], v[88:89], v[158:159] op_sel_hi:[1,0]
	v_pk_mul_f32 v[90:91], v[90:91], v[158:159] op_sel_hi:[1,0]
	s_cbranch_vccz .Lfe_nr2
	v_max_f32_e32 v92, 0, v92
	v_max_f32_e32 v93, 0, v93
	v_max_f32_e32 v94, 0, v94
	v_max_f32_e32 v95, 0, v95
	v_max_f32_e32 v96, 0, v96
	v_max_f32_e32 v97, 0, v97
	v_max_f32_e32 v98, 0, v98
	v_max_f32_e32 v99, 0, v99
	v_max_f32_e32 v84, 0, v84
	v_max_f32_e32 v85, 0, v85
	v_max_f32_e32 v86, 0, v86
	v_max_f32_e32 v87, 0, v87
	v_max_f32_e32 v88, 0, v88
	v_max_f32_e32 v89, 0, v89
	v_max_f32_e32 v90, 0, v90
	v_max_f32_e32 v91, 0, v91
	v_pk_mul_f32 v[92:93], v[92:93], v[92:93]
	v_pk_mul_f32 v[94:95], v[94:95], v[94:95]
	v_pk_mul_f32 v[96:97], v[96:97], v[96:97]
	v_pk_mul_f32 v[98:99], v[98:99], v[98:99]
	v_pk_mul_f32 v[84:85], v[84:85], v[84:85]
	v_pk_mul_f32 v[86:87], v[86:87], v[86:87]
	v_pk_mul_f32 v[88:89], v[88:89], v[88:89]
	v_pk_mul_f32 v[90:91], v[90:91], v[90:91]
; __device__ __forceinline__ unsigned pk2(float lo, float hi) { const f32x2 v = {lo, hi}; return __builtin_bit_cast(unsigned, __builtin_convertvector(v, bf16x2_t)); }
;     __device__ __forceinline__ void operator()(const f32x4 (&acc)[2][2][4][2], const Unit& u, int wr, int wc, int fr, int fq) const {
;     ...
;             for (int m = 0; m < 4; ++m) {
;                 const int row = u.pm * BM + ai * HALF + wr * 64 + m * 16 + fr;
;                 const float rsc = P.rowscale ? P.scal * P.rowscale[row] : P.scal;
;                 float ss = 0.f;
; #pragma unroll
;                 for (int bj = 0; bj < 2; ++bj) {
;                     const int col = colbase + bj * HALF;
;                     f32x4 v0 = acc[ai][bj][m][0] * rsc, v1 = acc[ai][bj][m][1] * rsc;
;                     if (P.colscale) { const f32x4 c0 = *(const f32x4*)(P.colscale + col), c1 = *(const f32x4*)(P.colscale + col + 4); v0 = v0 * c0; v1 = v1 * c1; }
;                     if (P.act == 1) {
; #pragma unroll
;                         for (int j = 0; j < 4; ++j) { const float a0 = v0[j] > 0.f ? v0[j] : 0.f, a1 = v1[j] > 0.f ? v1[j] : 0.f; v0[j] = a0 * a0; v1[j] = a1 * a1; }
;                     }
;                     bf16_t* dst = (row < P.split ? P.Olo : P.O) + (size_t)row * P.ldc + col;
;                     if (P.act == 2) {
;                         if (grp < 4) {
;                             const int bc = col - grp * 512;
;                             const f32x4 c0 = *(const f32x4*)(bias + bc), c1 = *(const f32x4*)(bias + bc + 4);
;                             const float mul = grp < 2 ? -0.60653066f : 1.0f;
; #pragma unroll
;                             for (int j = 0; j < 4; ++j) { v0[j] = mul * sigmoidf_(v0[j] + c0[j]); v1[j] = mul * sigmoidf_(v1[j] + c1[j]); }
;                         } else dst = P.O2 + (size_t)row * 512 + (col - 2048);
;                     }
;                     if (P.ssq) ss += (v0[0] * v0[0] + v0[1] * v0[1]) + (v0[2] * v0[2] + v0[3] * v0[3]) + (v1[0] * v1[0] + v1[1] * v1[1]) + (v1[2] * v1[2] + v1[3] * v1[3]);
;                     if (col < P.ncols) { u32x4 w; w.x = pk2(v0[0], v0[1]); w.y = pk2(v0[2], v0[3]); w.z = pk2(v1[0], v1[1]); w.w = pk2(v1[2], v1[3]);
;                         if (P.ldc >= 3504) __builtin_nontemporal_store(w, (u32x4*)dst); else *(u32x4*)dst = w; }
.Lfe_nr2:
	v_cvt_pk_bf16_f32 v96, v96, v97
	v_cvt_pk_bf16_f32 v97, v98, v99
	v_cvt_pk_bf16_f32 v98, v92, v93
	v_cvt_pk_bf16_f32 v99, v94, v95
	v_cvt_pk_bf16_f32 v88, v88, v89
	v_cvt_pk_bf16_f32 v89, v90, v91
	v_cvt_pk_bf16_f32 v90, v84, v85
	v_cvt_pk_bf16_f32 v91, v86, v87
	s_mov_b64 exec, s[18:19]
	global_store_dwordx4 v152, v[96:99], s[56:57]
	s_mov_b64 exec, s[20:21]
	global_store_dwordx4 v152, v[88:91], s[56:57] offset:256
	s_mov_b64 exec, s[14:15]
	v_mul_f32_e32 v158, s44, v205
	v_pk_mul_f32 v[76:77], v[76:77], v[158:159] op_sel_hi:[1,0]
	v_pk_mul_f32 v[78:79], v[78:79], v[158:159] op_sel_hi:[1,0]
	v_pk_mul_f32 v[80:81], v[80:81], v[158:159] op_sel_hi:[1,0]
	v_pk_mul_f32 v[82:83], v[82:83], v[158:159] op_sel_hi:[1,0]
	v_pk_mul_f32 v[68:69], v[68:69], v[158:159] op_sel_hi:[1,0]
	v_pk_mul_f32 v[70:71], v[70:71], v[158:159] op_sel_hi:[1,0]
	v_pk_mul_f32 v[72:73], v[72:73], v[158:159] op_sel_hi:[1,0]
	v_pk_mul_f32 v[74:75], v[74:75], v[158:159] op_sel_hi:[1,0]
	s_cbranch_vccz .Lfe_nr3
	v_max_f32_e32 v76, 0, v76
	v_max_f32_e32 v77, 0, v77
	v_max_f32_e32 v78, 0, v78
	v_max_f32_e32 v79, 0, v79
	v_max_f32_e32 v80, 0, v80
	v_max_f32_e32 v81, 0, v81
	v_max_f32_e32 v82, 0, v82
	v_max_f32_e32 v83, 0, v83
	v_max_f32_e32 v68, 0, v68
	v_max_f32_e32 v69, 0, v69
	v_max_f32_e32 v70, 0, v70
	v_max_f32_e32 v71, 0, v71
	v_max_f32_e32 v72, 0, v72
	v_max_f32_e32 v73, 0, v73
	v_max_f32_e32 v74, 0, v74
	v_max_f32_e32 v75, 0, v75
	v_pk_mul_f32 v[76:77], v[76:77], v[76:77]
	v_pk_mul_f32 v[78:79], v[78:79], v[78:79]
	v_pk_mul_f32 v[80:81], v[80:81], v[80:81]
	v_pk_mul_f32 v[82:83], v[82:83], v[82:83]
	v_pk_mul_f32 v[68:69], v[68:69], v[68:69]
	v_pk_mul_f32 v[70:71], v[70:71], v[70:71]
	v_pk_mul_f32 v[72:73], v[72:73], v[72:73]
	v_pk_mul_f32 v[74:75], v[74:75], v[74:75]
.Lfe_nr3:
	v_cvt_pk_bf16_f32 v80, v80, v81
	v_cvt_pk_bf16_f32 v81, v82, v83
	v_cvt_pk_bf16_f32 v82, v76, v77
	v_cvt_pk_bf16_f32 v83, v78, v79
	v_cvt_pk_bf16_f32 v72, v72, v73
	v_cvt_pk_bf16_f32 v73, v74, v75
	v_cvt_pk_bf16_f32 v74, v68, v69
	v_cvt_pk_bf16_f32 v75, v70, v71
	s_mov_b64 exec, s[18:19]
	global_store_dwordx4 v153, v[80:83], s[56:57]
	s_mov_b64 exec, s[20:21]
	global_store_dwordx4 v153, v[72:75], s[56:57] offset:256
	s_mov_b64 exec, s[14:15]
	v_mul_f32_e32 v158, s44, v206
	v_pk_mul_f32 v[60:61], v[60:61], v[158:159] op_sel_hi:[1,0]
	v_pk_mul_f32 v[62:63], v[62:63], v[158:159] op_sel_hi:[1,0]
	v_pk_mul_f32 v[64:65], v[64:65], v[158:159] op_sel_hi:[1,0]
	v_pk_mul_f32 v[66:67], v[66:67], v[158:159] op_sel_hi:[1,0]
	v_pk_mul_f32 v[52:53], v[52:53], v[158:159] op_sel_hi:[1,0]
	v_pk_mul_f32 v[54:55], v[54:55], v[158:159] op_sel_hi:[1,0]
	v_pk_mul_f32 v[56:57], v[56:57], v[158:159] op_sel_hi:[1,0]
	v_pk_mul_f32 v[58:59], v[58:59], v[158:159] op_sel_hi:[1,0]
	s_cbranch_vccz .Lfe_nr4
	v_max_f32_e32 v60, 0, v60
	v_max_f32_e32 v61, 0, v61
	v_max_f32_e32 v62, 0, v62
	v_max_f32_e32 v63, 0, v63
	v_max_f32_e32 v64, 0, v64
	v_max_f32_e32 v65, 0, v65
	v_max_f32_e32 v66, 0, v66
	v_max_f32_e32 v67, 0, v67
	v_max_f32_e32 v52, 0, v52
	v_max_f32_e32 v53, 0, v53
	v_max_f32_e32 v54, 0, v54
	v_max_f32_e32 v55, 0, v55
	v_max_f32_e32 v56, 0, v56
	v_max_f32_e32 v57, 0, v57
	v_max_f32_e32 v58, 0, v58
	v_max_f32_e32 v59, 0, v59
	v_pk_mul_f32 v[60:61], v[60:61], v[60:61]
	v_pk_mul_f32 v[62:63], v[62:63], v[62:63]
	v_pk_mul_f32 v[64:65], v[64:65], v[64:65]
	v_pk_mul_f32 v[66:67], v[66:67], v[66:67]
	v_pk_mul_f32 v[52:53], v[52:53], v[52:53]
	v_pk_mul_f32 v[54:55], v[54:55], v[54:55]
	v_pk_mul_f32 v[56:57], v[56:57], v[56:57]
	v_pk_mul_f32 v[58:59], v[58:59], v[58:59]
.Lfe_nr4:
	v_cvt_pk_bf16_f32 v64, v64, v65
	v_cvt_pk_bf16_f32 v65, v66, v67
	v_cvt_pk_bf16_f32 v66, v60, v61
	v_cvt_pk_bf16_f32 v67, v62, v63
	v_cvt_pk_bf16_f32 v56, v56, v57
	v_cvt_pk_bf16_f32 v57, v58, v59
	v_cvt_pk_bf16_f32 v58, v52, v53
	v_cvt_pk_bf16_f32 v59, v54, v55
	s_mov_b64 exec, s[18:19]
	global_store_dwordx4 v154, v[64:67], s[56:57]
	s_mov_b64 exec, s[20:21]
	global_store_dwordx4 v154, v[56:59], s[56:57] offset:256
	s_mov_b64 exec, s[14:15]
	v_mul_f32_e32 v158, s44, v207
	v_pk_mul_f32 v[44:45], v[44:45], v[158:159] op_sel_hi:[1,0]
	v_pk_mul_f32 v[46:47], v[46:47], v[158:159] op_sel_hi:[1,0]
	v_pk_mul_f32 v[48:49], v[48:49], v[158:159] op_sel_hi:[1,0]
	v_pk_mul_f32 v[50:51], v[50:51], v[158:159] op_sel_hi:[1,0]
	v_pk_mul_f32 v[36:37], v[36:37], v[158:159] op_sel_hi:[1,0]
	v_pk_mul_f32 v[38:39], v[38:39], v[158:159] op_sel_hi:[1,0]
	v_pk_mul_f32 v[40:41], v[40:41], v[158:159] op_sel_hi:[1,0]
	v_pk_mul_f32 v[42:43], v[42:43], v[158:159] op_sel_hi:[1,0]
	s_cbranch_vccz .Lfe_nr5
	v_max_f32_e32 v44, 0, v44
	v_max_f32_e32 v45, 0, v45
	v_max_f32_e32 v46, 0, v46
	v_max_f32_e32 v47, 0, v47
	v_max_f32_e32 v48, 0, v48
	v_max_f32_e32 v49, 0, v49
	v_max_f32_e32 v50, 0, v50
	v_max_f32_e32 v51, 0, v51
	v_max_f32_e32 v36, 0, v36
	v_max_f32_e32 v37, 0, v37
	v_max_f32_e32 v38, 0, v38
	v_max_f32_e32 v39, 0, v39
	v_max_f32_e32 v40, 0, v40
	v_max_f32_e32 v41, 0, v41
	v_max_f32_e32 v42, 0, v42
	v_max_f32_e32 v43, 0, v43
	v_pk_mul_f32 v[44:45], v[44:45], v[44:45]
	v_pk_mul_f32 v[46:47], v[46:47], v[46:47]
	v_pk_mul_f32 v[48:49], v[48:49], v[48:49]
	v_pk_mul_f32 v[50:51], v[50:51], v[50:51]
	v_pk_mul_f32 v[36:37], v[36:37], v[36:37]
	v_pk_mul_f32 v[38:39], v[38:39], v[38:39]
	v_pk_mul_f32 v[40:41], v[40:41], v[40:41]
	v_pk_mul_f32 v[42:43], v[42:43], v[42:43]
; __device__ __forceinline__ unsigned pk2(float lo, float hi) { const f32x2 v = {lo, hi}; return __builtin_bit_cast(unsigned, __builtin_convertvector(v, bf16x2_t)); }
;     __device__ __forceinline__ void operator()(const f32x4 (&acc)[2][2][4][2], const Unit& u, int wr, int wc, int fr, int fq) const {
;     ...
;             for (int m = 0; m < 4; ++m) {
;                 const int row = u.pm * BM + ai * HALF + wr * 64 + m * 16 + fr;
;                 const float rsc = P.rowscale ? P.scal * P.rowscale[row] : P.scal;
;                 float ss = 0.f;
; #pragma unroll
;                 for (int bj = 0; bj < 2; ++bj) {
;                     const int col = colbase + bj * HALF;
;                     f32x4 v0 = acc[ai][bj][m][0] * rsc, v1 = acc[ai][bj][m][1] * rsc;
;                     if (P.colscale) { const f32x4 c0 = *(const f32x4*)(P.colscale + col), c1 = *(const f32x4*)(P.colscale + col + 4); v0 = v0 * c0; v1 = v1 * c1; }
;                     if (P.act == 1) {
; #pragma unroll
;                         for (int j = 0; j < 4; ++j) { const float a0 = v0[j] > 0.f ? v0[j] : 0.f, a1 = v1[j] > 0.f ? v1[j] : 0.f; v0[j] = a0 * a0; v1[j] = a1 * a1; }
;                     }
;                     bf16_t* dst = (row < P.split ? P.Olo : P.O) + (size_t)row * P.ldc + col;
;                     if (P.act == 2) {
;                         if (grp < 4) {
;                             const int bc = col - grp * 512;
;                             const f32x4 c0 = *(const f32x4*)(bias + bc), c1 = *(const f32x4*)(bias + bc + 4);
;                             const float mul = grp < 2 ? -0.60653066f : 1.0f;
; #pragma unroll
;                             for (int j = 0; j < 4; ++j) { v0[j] = mul * sigmoidf_(v0[j] + c0[j]); v1[j] = mul * sigmoidf_(v1[j] + c1[j]); }
;                         } else dst = P.O2 + (size_t)row * 512 + (col - 2048);
;                     }
;                     if (P.ssq) ss += (v0[0] * v0[0] + v0[1] * v0[1]) + (v0[2] * v0[2] + v0[3] * v0[3]) + (v1[0] * v1[0] + v1[1] * v1[1]) + (v1[2] * v1[2] + v1[3] * v1[3]);
;                     if (col < P.ncols) { u32x4 w; w.x = pk2(v0[0], v0[1]); w.y = pk2(v0[2], v0[3]); w.z = pk2(v1[0], v1[1]); w.w = pk2(v1[2], v1[3]);
;                         if (P.ldc >= 3504) __builtin_nontemporal_store(w, (u32x4*)dst); else *(u32x4*)dst = w; }
.Lfe_nr5:
	v_cvt_pk_bf16_f32 v48, v48, v49
	v_cvt_pk_bf16_f32 v49, v50, v51
	v_cvt_pk_bf16_f32 v50, v44, v45
	v_cvt_pk_bf16_f32 v51, v46, v47
	v_cvt_pk_bf16_f32 v40, v40, v41
	v_cvt_pk_bf16_f32 v41, v42, v43
	v_cvt_pk_bf16_f32 v42, v36, v37
	v_cvt_pk_bf16_f32 v43, v38, v39
	s_mov_b64 exec, s[18:19]
	global_store_dwordx4 v155, v[48:51], s[56:57]
	s_mov_b64 exec, s[20:21]
	global_store_dwordx4 v155, v[40:43], s[56:57] offset:256
	s_mov_b64 exec, s[14:15]
	v_mul_f32_e32 v158, s44, v208
	v_pk_mul_f32 v[28:29], v[28:29], v[158:159] op_sel_hi:[1,0]
	v_pk_mul_f32 v[30:31], v[30:31], v[158:159] op_sel_hi:[1,0]
	v_pk_mul_f32 v[32:33], v[32:33], v[158:159] op_sel_hi:[1,0]
	v_pk_mul_f32 v[34:35], v[34:35], v[158:159] op_sel_hi:[1,0]
	v_pk_mul_f32 v[20:21], v[20:21], v[158:159] op_sel_hi:[1,0]
	v_pk_mul_f32 v[22:23], v[22:23], v[158:159] op_sel_hi:[1,0]
	v_pk_mul_f32 v[24:25], v[24:25], v[158:159] op_sel_hi:[1,0]
	v_pk_mul_f32 v[26:27], v[26:27], v[158:159] op_sel_hi:[1,0]
	s_cbranch_vccz .Lfe_nr6
	v_max_f32_e32 v28, 0, v28
	v_max_f32_e32 v29, 0, v29
	v_max_f32_e32 v30, 0, v30
	v_max_f32_e32 v31, 0, v31
	v_max_f32_e32 v32, 0, v32
	v_max_f32_e32 v33, 0, v33
	v_max_f32_e32 v34, 0, v34
	v_max_f32_e32 v35, 0, v35
	v_max_f32_e32 v20, 0, v20
	v_max_f32_e32 v21, 0, v21
	v_max_f32_e32 v22, 0, v22
	v_max_f32_e32 v23, 0, v23
	v_max_f32_e32 v24, 0, v24
	v_max_f32_e32 v25, 0, v25
	v_max_f32_e32 v26, 0, v26
	v_max_f32_e32 v27, 0, v27
	v_pk_mul_f32 v[28:29], v[28:29], v[28:29]
	v_pk_mul_f32 v[30:31], v[30:31], v[30:31]
	v_pk_mul_f32 v[32:33], v[32:33], v[32:33]
	v_pk_mul_f32 v[34:35], v[34:35], v[34:35]
	v_pk_mul_f32 v[20:21], v[20:21], v[20:21]
	v_pk_mul_f32 v[22:23], v[22:23], v[22:23]
	v_pk_mul_f32 v[24:25], v[24:25], v[24:25]
	v_pk_mul_f32 v[26:27], v[26:27], v[26:27]
.Lfe_nr6:
	v_cvt_pk_bf16_f32 v32, v32, v33
	v_cvt_pk_bf16_f32 v33, v34, v35
	v_cvt_pk_bf16_f32 v34, v28, v29
	v_cvt_pk_bf16_f32 v35, v30, v31
	v_cvt_pk_bf16_f32 v24, v24, v25
	v_cvt_pk_bf16_f32 v25, v26, v27
	v_cvt_pk_bf16_f32 v26, v20, v21
	v_cvt_pk_bf16_f32 v27, v22, v23
	s_mov_b64 exec, s[18:19]
	global_store_dwordx4 v156, v[32:35], s[56:57]
	s_mov_b64 exec, s[20:21]
	global_store_dwordx4 v156, v[24:27], s[56:57] offset:256
	s_mov_b64 exec, s[14:15]
	v_mul_f32_e32 v158, s44, v209
	v_pk_mul_f32 v[8:9], v[8:9], v[158:159] op_sel_hi:[1,0]
	v_pk_mul_f32 v[10:11], v[10:11], v[158:159] op_sel_hi:[1,0]
	v_pk_mul_f32 v[12:13], v[12:13], v[158:159] op_sel_hi:[1,0]
	v_pk_mul_f32 v[14:15], v[14:15], v[158:159] op_sel_hi:[1,0]
	v_pk_mul_f32 v[0:1], v[0:1], v[158:159] op_sel_hi:[1,0]
	v_pk_mul_f32 v[2:3], v[2:3], v[158:159] op_sel_hi:[1,0]
	v_pk_mul_f32 v[4:5], v[4:5], v[158:159] op_sel_hi:[1,0]
	v_pk_mul_f32 v[6:7], v[6:7], v[158:159] op_sel_hi:[1,0]
	s_cbranch_vccz .Lfe_nr7
	v_max_f32_e32 v8, 0, v8
	v_max_f32_e32 v9, 0, v9
	v_max_f32_e32 v10, 0, v10
	v_max_f32_e32 v11, 0, v11
	v_max_f32_e32 v12, 0, v12
	v_max_f32_e32 v13, 0, v13
	v_max_f32_e32 v14, 0, v14
	v_max_f32_e32 v15, 0, v15
	v_max_f32_e32 v0, 0, v0
	v_max_f32_e32 v1, 0, v1
	v_max_f32_e32 v2, 0, v2
	v_max_f32_e32 v3, 0, v3
	v_max_f32_e32 v4, 0, v4
	v_max_f32_e32 v5, 0, v5
	v_max_f32_e32 v6, 0, v6
	v_max_f32_e32 v7, 0, v7
	v_pk_mul_f32 v[8:9], v[8:9], v[8:9]
	v_pk_mul_f32 v[10:11], v[10:11], v[10:11]
	v_pk_mul_f32 v[12:13], v[12:13], v[12:13]
	v_pk_mul_f32 v[14:15], v[14:15], v[14:15]
	v_pk_mul_f32 v[0:1], v[0:1], v[0:1]
	v_pk_mul_f32 v[2:3], v[2:3], v[2:3]
	v_pk_mul_f32 v[4:5], v[4:5], v[4:5]
	v_pk_mul_f32 v[6:7], v[6:7], v[6:7]
.Lfe_nr7:
	v_cvt_pk_bf16_f32 v12, v12, v13
	v_cvt_pk_bf16_f32 v13, v14, v15
	v_cvt_pk_bf16_f32 v14, v8, v9
	v_cvt_pk_bf16_f32 v15, v10, v11
	v_cvt_pk_bf16_f32 v4, v4, v5
	v_cvt_pk_bf16_f32 v5, v6, v7
	v_cvt_pk_bf16_f32 v6, v0, v1
	v_cvt_pk_bf16_f32 v7, v2, v3
	s_mov_b64 exec, s[18:19]
	global_store_dwordx4 v157, v[12:15], s[56:57]
	s_mov_b64 exec, s[20:21]
	global_store_dwordx4 v157, v[4:7], s[56:57] offset:256
	s_mov_b64 exec, s[14:15]
	s_branch .LBB0_467

; __device__ __forceinline__ float sigmoidf_(float z) { return __builtin_amdgcn_rcpf(1.0f + __expf(-z)); }
;     __device__ __forceinline__ void operator()(const f32x4 (&acc)[2][2][4][2], const Unit& u, int wr, int wc, int fr, int fq) const {
;     ...
;                         if (grp < 4) {
;                             const int bc = col - grp * 512;
;                             const f32x4 c0 = *(const f32x4*)(bias + bc), c1 = *(const f32x4*)(bias + bc + 4);
;                             const float mul = grp < 2 ? -0.60653066f : 1.0f;
; #pragma unroll
;                             for (int j = 0; j < 4; ++j) { v0[j] = mul * sigmoidf_(v0[j] + c0[j]); v1[j] = mul * sigmoidf_(v1[j] + c1[j]); }
.LBB0_698:
	s_andn2_b64 vcc, exec, s[66:67]
	s_cbranch_vccnz .LBB0_756
	s_ashr_i32 s29, s7, 31
	v_mov_b32_e32 v121, s29
	v_subrev_co_u32_e32 v120, vcc, s7, v146
	s_nop 1
	v_subb_co_u32_e32 v121, vcc, v147, v121, vcc
	v_lshl_add_u64 v[126:127], v[120:121], 2, s[62:63]
	v_mov_b32_e32 v120, v218
	v_mov_b32_e32 v121, v219
	v_mov_b32_e32 v122, v220
	v_mov_b32_e32 v123, v221
	v_mov_b32_e32 v150, v222
	v_mov_b32_e32 v151, v223
	v_mov_b32_e32 v152, v224
	v_mov_b32_e32 v153, v225
	v_add_f32_e32 v104, v104, v120
	v_add_f32_e32 v100, v100, v150
	v_add_f32_e32 v105, v105, v121
	v_add_f32_e32 v101, v101, v151
	v_add_f32_e32 v106, v106, v122
	v_add_f32_e32 v102, v102, v152
	v_add_f32_e32 v107, v107, v123
	v_add_f32_e32 v103, v103, v153
	v_mul_f32_e32 v104, 0xbfb8aa3b, v104
	v_mul_f32_e32 v100, 0xbfb8aa3b, v100
	v_mul_f32_e32 v105, 0xbfb8aa3b, v105
	v_mul_f32_e32 v101, 0xbfb8aa3b, v101
	v_mul_f32_e32 v106, 0xbfb8aa3b, v106
	v_mul_f32_e32 v102, 0xbfb8aa3b, v102
	v_mul_f32_e32 v107, 0xbfb8aa3b, v107
	v_mul_f32_e32 v103, 0xbfb8aa3b, v103
	v_exp_f32_e32 v104, v104
	v_exp_f32_e32 v100, v100
	v_exp_f32_e32 v105, v105
	v_exp_f32_e32 v101, v101
	v_exp_f32_e32 v106, v106
	v_exp_f32_e32 v102, v102
	v_exp_f32_e32 v107, v107
	v_exp_f32_e32 v103, v103
	v_add_f32_e32 v104, 1.0, v104
	v_add_f32_e32 v120, 1.0, v100
	v_add_f32_e32 v105, 1.0, v105
	v_add_f32_e32 v121, 1.0, v101
	v_add_f32_e32 v106, 1.0, v106
	v_add_f32_e32 v122, 1.0, v102
	v_add_f32_e32 v107, 1.0, v107
	v_add_f32_e32 v123, 1.0, v103
	v_rcp_f32_e32 v100, v104
	v_rcp_f32_e32 v120, v120
	v_rcp_f32_e32 v101, v105
	v_rcp_f32_e32 v102, v106
	v_rcp_f32_e32 v103, v107
	v_rcp_f32_e32 v122, v122
	v_rcp_f32_e32 v123, v123
	v_rcp_f32_e32 v121, v121
	v_pk_mul_f32 v[106:107], v[124:125], v[102:103] op_sel_hi:[0,1]
	v_pk_mul_f32 v[104:105], v[124:125], v[100:101] op_sel_hi:[0,1]
	v_pk_mul_f32 v[102:103], v[124:125], v[122:123] op_sel_hi:[0,1]
	v_pk_mul_f32 v[100:101], v[124:125], v[120:121] op_sel_hi:[0,1]
	s_and_b64 vcc, exec, s[24:25]
	s_cbranch_vccz .LBB0_558
	s_branch .LBB0_757

; __device__ __forceinline__ float sigmoidf_(float z) { return __builtin_amdgcn_rcpf(1.0f + __expf(-z)); }
;     __device__ __forceinline__ void operator()(const f32x4 (&acc)[2][2][4][2], const Unit& u, int wr, int wc, int fr, int fq) const {
;     ...
;                         if (grp < 4) {
;                             const int bc = col - grp * 512;
;                             const f32x4 c0 = *(const f32x4*)(bias + bc), c1 = *(const f32x4*)(bias + bc + 4);
;                             const float mul = grp < 2 ? -0.60653066f : 1.0f;
; #pragma unroll
;                             for (int j = 0; j < 4; ++j) { v0[j] = mul * sigmoidf_(v0[j] + c0[j]); v1[j] = mul * sigmoidf_(v1[j] + c1[j]); }
.LBB0_703:
	s_andn2_b64 vcc, exec, s[66:67]
	s_cbranch_vccnz .LBB0_758
	s_ashr_i32 s29, s7, 31
	v_mov_b32_e32 v103, s29
	v_subrev_co_u32_e32 v102, vcc, s7, v146
	s_nop 1
	v_subb_co_u32_e32 v103, vcc, v147, v103, vcc
	v_lshl_add_u64 v[106:107], v[102:103], 2, s[62:63]
	v_mov_b32_e32 v102, v218
	v_mov_b32_e32 v103, v219
	v_mov_b32_e32 v104, v220
	v_mov_b32_e32 v105, v221
	v_mov_b32_e32 v106, v222
	v_mov_b32_e32 v107, v223
	v_mov_b32_e32 v108, v224
	v_mov_b32_e32 v109, v225
	v_add_f32_e32 v88, v88, v102
	v_add_f32_e32 v84, v84, v106
	v_add_f32_e32 v89, v89, v103
	v_add_f32_e32 v85, v85, v107
	v_add_f32_e32 v90, v90, v104
	v_add_f32_e32 v86, v86, v108
	v_add_f32_e32 v91, v91, v105
	v_add_f32_e32 v87, v87, v109
	v_mul_f32_e32 v88, 0xbfb8aa3b, v88
	v_mul_f32_e32 v84, 0xbfb8aa3b, v84
	v_mul_f32_e32 v89, 0xbfb8aa3b, v89
	v_mul_f32_e32 v85, 0xbfb8aa3b, v85
	v_mul_f32_e32 v90, 0xbfb8aa3b, v90
	v_mul_f32_e32 v86, 0xbfb8aa3b, v86
	v_mul_f32_e32 v91, 0xbfb8aa3b, v91
	v_mul_f32_e32 v87, 0xbfb8aa3b, v87
	v_exp_f32_e32 v88, v88
	v_exp_f32_e32 v84, v84
	v_exp_f32_e32 v89, v89
	v_exp_f32_e32 v85, v85
	v_exp_f32_e32 v90, v90
	v_exp_f32_e32 v86, v86
	v_exp_f32_e32 v91, v91
	v_exp_f32_e32 v87, v87
	v_add_f32_e32 v88, 1.0, v88
	v_add_f32_e32 v102, 1.0, v84
	v_add_f32_e32 v89, 1.0, v89
	v_add_f32_e32 v103, 1.0, v85
	v_add_f32_e32 v90, 1.0, v90
	v_add_f32_e32 v104, 1.0, v86
	v_add_f32_e32 v91, 1.0, v91
	v_add_f32_e32 v105, 1.0, v87
	v_rcp_f32_e32 v84, v88
	v_rcp_f32_e32 v102, v102
	v_rcp_f32_e32 v85, v89
	v_rcp_f32_e32 v86, v90
	v_rcp_f32_e32 v87, v91
	v_rcp_f32_e32 v104, v104
	v_rcp_f32_e32 v105, v105
	v_rcp_f32_e32 v103, v103
	v_pk_mul_f32 v[90:91], v[124:125], v[86:87] op_sel_hi:[0,1]
	v_pk_mul_f32 v[88:89], v[124:125], v[84:85] op_sel_hi:[0,1]
	v_pk_mul_f32 v[86:87], v[124:125], v[104:105] op_sel_hi:[0,1]
	v_pk_mul_f32 v[84:85], v[124:125], v[102:103] op_sel_hi:[0,1]
	s_and_b64 vcc, exec, s[24:25]
	s_cbranch_vccz .LBB0_580
	s_branch .LBB0_759

; __device__ __forceinline__ float sigmoidf_(float z) { return __builtin_amdgcn_rcpf(1.0f + __expf(-z)); }
;     __device__ __forceinline__ void operator()(const f32x4 (&acc)[2][2][4][2], const Unit& u, int wr, int wc, int fr, int fq) const {
;     ...
;                         if (grp < 4) {
;                             const int bc = col - grp * 512;
;                             const f32x4 c0 = *(const f32x4*)(bias + bc), c1 = *(const f32x4*)(bias + bc + 4);
;                             const float mul = grp < 2 ? -0.60653066f : 1.0f;
; #pragma unroll
;                             for (int j = 0; j < 4; ++j) { v0[j] = mul * sigmoidf_(v0[j] + c0[j]); v1[j] = mul * sigmoidf_(v1[j] + c1[j]); }
.LBB0_708:
	s_andn2_b64 vcc, exec, s[66:67]
	s_cbranch_vccnz .LBB0_760
	s_ashr_i32 s29, s7, 31
	v_mov_b32_e32 v87, s29
	v_subrev_co_u32_e32 v86, vcc, s7, v146
	s_nop 1
	v_subb_co_u32_e32 v87, vcc, v147, v87, vcc
	v_lshl_add_u64 v[90:91], v[86:87], 2, s[62:63]
	v_mov_b32_e32 v86, v218
	v_mov_b32_e32 v87, v219
	v_mov_b32_e32 v88, v220
	v_mov_b32_e32 v89, v221
	v_mov_b32_e32 v90, v222
	v_mov_b32_e32 v91, v223
	v_mov_b32_e32 v92, v224
	v_mov_b32_e32 v93, v225
	v_add_f32_e32 v72, v72, v86
	v_add_f32_e32 v68, v68, v90
	v_add_f32_e32 v73, v73, v87
	v_add_f32_e32 v69, v69, v91
	v_add_f32_e32 v74, v74, v88
	v_add_f32_e32 v70, v70, v92
	v_add_f32_e32 v75, v75, v89
	v_add_f32_e32 v71, v71, v93
	v_mul_f32_e32 v72, 0xbfb8aa3b, v72
	v_mul_f32_e32 v68, 0xbfb8aa3b, v68
	v_mul_f32_e32 v73, 0xbfb8aa3b, v73
	v_mul_f32_e32 v69, 0xbfb8aa3b, v69
	v_mul_f32_e32 v74, 0xbfb8aa3b, v74
	v_mul_f32_e32 v70, 0xbfb8aa3b, v70
	v_mul_f32_e32 v75, 0xbfb8aa3b, v75
	v_mul_f32_e32 v71, 0xbfb8aa3b, v71
	v_exp_f32_e32 v72, v72
	v_exp_f32_e32 v68, v68
	v_exp_f32_e32 v73, v73
	v_exp_f32_e32 v69, v69
	v_exp_f32_e32 v74, v74
	v_exp_f32_e32 v70, v70
	v_exp_f32_e32 v75, v75
	v_exp_f32_e32 v71, v71
	v_add_f32_e32 v72, 1.0, v72
	v_add_f32_e32 v86, 1.0, v68
	v_add_f32_e32 v73, 1.0, v73
	v_add_f32_e32 v87, 1.0, v69
	v_add_f32_e32 v74, 1.0, v74
	v_add_f32_e32 v88, 1.0, v70
	v_add_f32_e32 v75, 1.0, v75
	v_add_f32_e32 v89, 1.0, v71
	v_rcp_f32_e32 v68, v72
	v_rcp_f32_e32 v86, v86
	v_rcp_f32_e32 v69, v73
	v_rcp_f32_e32 v70, v74
	v_rcp_f32_e32 v71, v75
	v_rcp_f32_e32 v88, v88
	v_rcp_f32_e32 v89, v89
	v_rcp_f32_e32 v87, v87
	v_pk_mul_f32 v[74:75], v[124:125], v[70:71] op_sel_hi:[0,1]
	v_pk_mul_f32 v[72:73], v[124:125], v[68:69] op_sel_hi:[0,1]
	v_pk_mul_f32 v[70:71], v[124:125], v[88:89] op_sel_hi:[0,1]
	v_pk_mul_f32 v[68:69], v[124:125], v[86:87] op_sel_hi:[0,1]
	s_and_b64 vcc, exec, s[24:25]
	s_cbranch_vccz .LBB0_602
	s_branch .LBB0_761

; __device__ __forceinline__ float sigmoidf_(float z) { return __builtin_amdgcn_rcpf(1.0f + __expf(-z)); }
;     __device__ __forceinline__ void operator()(const f32x4 (&acc)[2][2][4][2], const Unit& u, int wr, int wc, int fr, int fq) const {
;     ...
;                         if (grp < 4) {
;                             const int bc = col - grp * 512;
;                             const f32x4 c0 = *(const f32x4*)(bias + bc), c1 = *(const f32x4*)(bias + bc + 4);
;                             const float mul = grp < 2 ? -0.60653066f : 1.0f;
; #pragma unroll
;                             for (int j = 0; j < 4; ++j) { v0[j] = mul * sigmoidf_(v0[j] + c0[j]); v1[j] = mul * sigmoidf_(v1[j] + c1[j]); }
.LBB0_713:
	s_andn2_b64 vcc, exec, s[66:67]
	s_cbranch_vccnz .LBB0_762
	s_ashr_i32 s29, s7, 31
	v_mov_b32_e32 v71, s29
	v_subrev_co_u32_e32 v70, vcc, s7, v146
	s_nop 1
	v_subb_co_u32_e32 v71, vcc, v147, v71, vcc
	v_lshl_add_u64 v[74:75], v[70:71], 2, s[62:63]
	v_mov_b32_e32 v70, v218
	v_mov_b32_e32 v71, v219
	v_mov_b32_e32 v72, v220
	v_mov_b32_e32 v73, v221
	v_mov_b32_e32 v74, v222
	v_mov_b32_e32 v75, v223
	v_mov_b32_e32 v76, v224
	v_mov_b32_e32 v77, v225
	v_add_f32_e32 v56, v56, v70
	v_add_f32_e32 v52, v52, v74
	v_add_f32_e32 v57, v57, v71
	v_add_f32_e32 v53, v53, v75
	v_add_f32_e32 v58, v58, v72
	v_add_f32_e32 v54, v54, v76
	v_add_f32_e32 v59, v59, v73
	v_add_f32_e32 v55, v55, v77
	v_mul_f32_e32 v56, 0xbfb8aa3b, v56
	v_mul_f32_e32 v52, 0xbfb8aa3b, v52
	v_mul_f32_e32 v57, 0xbfb8aa3b, v57
	v_mul_f32_e32 v53, 0xbfb8aa3b, v53
	v_mul_f32_e32 v58, 0xbfb8aa3b, v58
	v_mul_f32_e32 v54, 0xbfb8aa3b, v54
	v_mul_f32_e32 v59, 0xbfb8aa3b, v59
	v_mul_f32_e32 v55, 0xbfb8aa3b, v55
	v_exp_f32_e32 v56, v56
	v_exp_f32_e32 v52, v52
	v_exp_f32_e32 v57, v57
	v_exp_f32_e32 v53, v53
	v_exp_f32_e32 v58, v58
	v_exp_f32_e32 v54, v54
	v_exp_f32_e32 v59, v59
	v_exp_f32_e32 v55, v55
	v_add_f32_e32 v56, 1.0, v56
	v_add_f32_e32 v70, 1.0, v52
	v_add_f32_e32 v57, 1.0, v57
	v_add_f32_e32 v71, 1.0, v53
	v_add_f32_e32 v58, 1.0, v58
	v_add_f32_e32 v72, 1.0, v54
	v_add_f32_e32 v59, 1.0, v59
	v_add_f32_e32 v73, 1.0, v55
	v_rcp_f32_e32 v52, v56
	v_rcp_f32_e32 v70, v70
	v_rcp_f32_e32 v53, v57
	v_rcp_f32_e32 v54, v58
	v_rcp_f32_e32 v55, v59
	v_rcp_f32_e32 v72, v72
	v_rcp_f32_e32 v73, v73
	v_rcp_f32_e32 v71, v71
	v_pk_mul_f32 v[58:59], v[124:125], v[54:55] op_sel_hi:[0,1]
	v_pk_mul_f32 v[56:57], v[124:125], v[52:53] op_sel_hi:[0,1]
	v_pk_mul_f32 v[54:55], v[124:125], v[72:73] op_sel_hi:[0,1]
	v_pk_mul_f32 v[52:53], v[124:125], v[70:71] op_sel_hi:[0,1]
	s_and_b64 vcc, exec, s[24:25]
	s_cbranch_vccz .LBB0_624
	s_branch .LBB0_763

; __device__ __forceinline__ float sigmoidf_(float z) { return __builtin_amdgcn_rcpf(1.0f + __expf(-z)); }
;     __device__ __forceinline__ void operator()(const f32x4 (&acc)[2][2][4][2], const Unit& u, int wr, int wc, int fr, int fq) const {
;     ...
;                         if (grp < 4) {
;                             const int bc = col - grp * 512;
;                             const f32x4 c0 = *(const f32x4*)(bias + bc), c1 = *(const f32x4*)(bias + bc + 4);
;                             const float mul = grp < 2 ? -0.60653066f : 1.0f;
; #pragma unroll
;                             for (int j = 0; j < 4; ++j) { v0[j] = mul * sigmoidf_(v0[j] + c0[j]); v1[j] = mul * sigmoidf_(v1[j] + c1[j]); }
.LBB0_718:
	s_andn2_b64 vcc, exec, s[66:67]
	s_cbranch_vccnz .LBB0_764
	s_ashr_i32 s29, s7, 31
	v_mov_b32_e32 v55, s29
	v_subrev_co_u32_e32 v54, vcc, s7, v146
	s_nop 1
	v_subb_co_u32_e32 v55, vcc, v147, v55, vcc
	v_lshl_add_u64 v[58:59], v[54:55], 2, s[62:63]
	v_mov_b32_e32 v54, v218
	v_mov_b32_e32 v55, v219
	v_mov_b32_e32 v56, v220
	v_mov_b32_e32 v57, v221
	v_mov_b32_e32 v58, v222
	v_mov_b32_e32 v59, v223
	v_mov_b32_e32 v60, v224
	v_mov_b32_e32 v61, v225
	v_add_f32_e32 v40, v40, v54
	v_add_f32_e32 v36, v36, v58
	v_add_f32_e32 v41, v41, v55
	v_add_f32_e32 v37, v37, v59
	v_add_f32_e32 v42, v42, v56
	v_add_f32_e32 v38, v38, v60
	v_add_f32_e32 v43, v43, v57
	v_add_f32_e32 v39, v39, v61
	v_mul_f32_e32 v40, 0xbfb8aa3b, v40
	v_mul_f32_e32 v36, 0xbfb8aa3b, v36
	v_mul_f32_e32 v41, 0xbfb8aa3b, v41
	v_mul_f32_e32 v37, 0xbfb8aa3b, v37
	v_mul_f32_e32 v42, 0xbfb8aa3b, v42
	v_mul_f32_e32 v38, 0xbfb8aa3b, v38
	v_mul_f32_e32 v43, 0xbfb8aa3b, v43
	v_mul_f32_e32 v39, 0xbfb8aa3b, v39
	v_exp_f32_e32 v40, v40
	v_exp_f32_e32 v36, v36
	v_exp_f32_e32 v41, v41
	v_exp_f32_e32 v37, v37
	v_exp_f32_e32 v42, v42
	v_exp_f32_e32 v38, v38
	v_exp_f32_e32 v43, v43
	v_exp_f32_e32 v39, v39
	v_add_f32_e32 v40, 1.0, v40
	v_add_f32_e32 v54, 1.0, v36
	v_add_f32_e32 v41, 1.0, v41
	v_add_f32_e32 v55, 1.0, v37
	v_add_f32_e32 v42, 1.0, v42
	v_add_f32_e32 v56, 1.0, v38
	v_add_f32_e32 v43, 1.0, v43
	v_add_f32_e32 v57, 1.0, v39
	v_rcp_f32_e32 v36, v40
	v_rcp_f32_e32 v54, v54
	v_rcp_f32_e32 v37, v41
	v_rcp_f32_e32 v38, v42
	v_rcp_f32_e32 v39, v43
	v_rcp_f32_e32 v56, v56
	v_rcp_f32_e32 v57, v57
	v_rcp_f32_e32 v55, v55
	v_pk_mul_f32 v[42:43], v[124:125], v[38:39] op_sel_hi:[0,1]
	v_pk_mul_f32 v[40:41], v[124:125], v[36:37] op_sel_hi:[0,1]
	v_pk_mul_f32 v[38:39], v[124:125], v[56:57] op_sel_hi:[0,1]
	v_pk_mul_f32 v[36:37], v[124:125], v[54:55] op_sel_hi:[0,1]
	s_and_b64 vcc, exec, s[24:25]
	s_cbranch_vccz .LBB0_646
	s_branch .LBB0_765

; __device__ __forceinline__ float sigmoidf_(float z) { return __builtin_amdgcn_rcpf(1.0f + __expf(-z)); }
;     __device__ __forceinline__ void operator()(const f32x4 (&acc)[2][2][4][2], const Unit& u, int wr, int wc, int fr, int fq) const {
;     ...
;                         if (grp < 4) {
;                             const int bc = col - grp * 512;
;                             const f32x4 c0 = *(const f32x4*)(bias + bc), c1 = *(const f32x4*)(bias + bc + 4);
;                             const float mul = grp < 2 ? -0.60653066f : 1.0f;
; #pragma unroll
;                             for (int j = 0; j < 4; ++j) { v0[j] = mul * sigmoidf_(v0[j] + c0[j]); v1[j] = mul * sigmoidf_(v1[j] + c1[j]); }
.LBB0_723:
	s_andn2_b64 vcc, exec, s[66:67]
	s_cbranch_vccnz .LBB0_766
	s_ashr_i32 s29, s7, 31
	v_mov_b32_e32 v39, s29
	v_subrev_co_u32_e32 v38, vcc, s7, v146
	s_nop 1
	v_subb_co_u32_e32 v39, vcc, v147, v39, vcc
	v_lshl_add_u64 v[42:43], v[38:39], 2, s[62:63]
	v_mov_b32_e32 v38, v218
	v_mov_b32_e32 v39, v219
	v_mov_b32_e32 v40, v220
	v_mov_b32_e32 v41, v221
	v_mov_b32_e32 v42, v222
	v_mov_b32_e32 v43, v223
	v_mov_b32_e32 v44, v224
	v_mov_b32_e32 v45, v225
	v_add_f32_e32 v24, v24, v38
	v_add_f32_e32 v20, v20, v42
	v_add_f32_e32 v25, v25, v39
	v_add_f32_e32 v21, v21, v43
	v_add_f32_e32 v26, v26, v40
	v_add_f32_e32 v22, v22, v44
	v_add_f32_e32 v27, v27, v41
	v_add_f32_e32 v23, v23, v45
	v_mul_f32_e32 v24, 0xbfb8aa3b, v24
	v_mul_f32_e32 v20, 0xbfb8aa3b, v20
	v_mul_f32_e32 v25, 0xbfb8aa3b, v25
	v_mul_f32_e32 v21, 0xbfb8aa3b, v21
	v_mul_f32_e32 v26, 0xbfb8aa3b, v26
	v_mul_f32_e32 v22, 0xbfb8aa3b, v22
	v_mul_f32_e32 v27, 0xbfb8aa3b, v27
	v_mul_f32_e32 v23, 0xbfb8aa3b, v23
	v_exp_f32_e32 v24, v24
	v_exp_f32_e32 v20, v20
	v_exp_f32_e32 v25, v25
	v_exp_f32_e32 v21, v21
	v_exp_f32_e32 v26, v26
	v_exp_f32_e32 v22, v22
	v_exp_f32_e32 v27, v27
	v_exp_f32_e32 v23, v23
	v_add_f32_e32 v24, 1.0, v24
	v_add_f32_e32 v38, 1.0, v20
	v_add_f32_e32 v25, 1.0, v25
	v_add_f32_e32 v39, 1.0, v21
	v_add_f32_e32 v26, 1.0, v26
	v_add_f32_e32 v40, 1.0, v22
	v_add_f32_e32 v27, 1.0, v27
	v_add_f32_e32 v41, 1.0, v23
	v_rcp_f32_e32 v20, v24
	v_rcp_f32_e32 v38, v38
	v_rcp_f32_e32 v21, v25
	v_rcp_f32_e32 v22, v26
	v_rcp_f32_e32 v23, v27
	v_rcp_f32_e32 v40, v40
	v_rcp_f32_e32 v41, v41
	v_rcp_f32_e32 v39, v39
	v_pk_mul_f32 v[26:27], v[124:125], v[22:23] op_sel_hi:[0,1]
	v_pk_mul_f32 v[24:25], v[124:125], v[20:21] op_sel_hi:[0,1]
	v_pk_mul_f32 v[22:23], v[124:125], v[40:41] op_sel_hi:[0,1]
	v_pk_mul_f32 v[20:21], v[124:125], v[38:39] op_sel_hi:[0,1]
	s_and_b64 vcc, exec, s[24:25]
	s_cbranch_vccz .LBB0_668
	s_branch .LBB0_767

; __device__ __forceinline__ float sigmoidf_(float z) { return __builtin_amdgcn_rcpf(1.0f + __expf(-z)); }
;     __device__ __forceinline__ void operator()(const f32x4 (&acc)[2][2][4][2], const Unit& u, int wr, int wc, int fr, int fq) const {
;     ...
;                         if (grp < 4) {
;                             const int bc = col - grp * 512;
;                             const f32x4 c0 = *(const f32x4*)(bias + bc), c1 = *(const f32x4*)(bias + bc + 4);
;                             const float mul = grp < 2 ? -0.60653066f : 1.0f;
; #pragma unroll
;                             for (int j = 0; j < 4; ++j) { v0[j] = mul * sigmoidf_(v0[j] + c0[j]); v1[j] = mul * sigmoidf_(v1[j] + c1[j]); }
.LBB0_728:
	s_andn2_b64 vcc, exec, s[12:13]
	s_cbranch_vccnz .LBB0_768
	s_ashr_i32 s12, s7, 31
	v_mov_b32_e32 v23, s12
	v_subrev_co_u32_e32 v22, vcc, s7, v146
	s_nop 1
	v_subb_co_u32_e32 v23, vcc, v147, v23, vcc
	v_lshl_add_u64 v[26:27], v[22:23], 2, s[62:63]
	v_mov_b32_e32 v22, v218
	v_mov_b32_e32 v23, v219
	v_mov_b32_e32 v24, v220
	v_mov_b32_e32 v25, v221
	v_mov_b32_e32 v26, v222
	v_mov_b32_e32 v27, v223
	v_mov_b32_e32 v28, v224
	v_mov_b32_e32 v29, v225
	v_add_f32_e32 v4, v4, v22
	v_add_f32_e32 v0, v0, v26
	v_add_f32_e32 v5, v5, v23
	v_add_f32_e32 v1, v1, v27
	v_add_f32_e32 v6, v6, v24
	v_add_f32_e32 v2, v2, v28
	v_add_f32_e32 v7, v7, v25
	v_add_f32_e32 v3, v3, v29
	v_mul_f32_e32 v4, 0xbfb8aa3b, v4
	v_mul_f32_e32 v0, 0xbfb8aa3b, v0
	v_mul_f32_e32 v5, 0xbfb8aa3b, v5
	v_mul_f32_e32 v1, 0xbfb8aa3b, v1
	v_mul_f32_e32 v6, 0xbfb8aa3b, v6
	v_mul_f32_e32 v2, 0xbfb8aa3b, v2
	v_mul_f32_e32 v7, 0xbfb8aa3b, v7
	v_mul_f32_e32 v3, 0xbfb8aa3b, v3
	v_exp_f32_e32 v4, v4
	v_exp_f32_e32 v0, v0
	v_exp_f32_e32 v5, v5
	v_exp_f32_e32 v1, v1
	v_exp_f32_e32 v6, v6
	v_exp_f32_e32 v2, v2
	v_exp_f32_e32 v7, v7
	v_exp_f32_e32 v3, v3
	v_add_f32_e32 v4, 1.0, v4
	v_add_f32_e32 v22, 1.0, v0
	v_add_f32_e32 v5, 1.0, v5
	v_add_f32_e32 v23, 1.0, v1
	v_add_f32_e32 v6, 1.0, v6
	v_add_f32_e32 v24, 1.0, v2
	v_add_f32_e32 v7, 1.0, v7
	v_add_f32_e32 v25, 1.0, v3
	v_rcp_f32_e32 v0, v4
	v_rcp_f32_e32 v22, v22
	v_rcp_f32_e32 v1, v5
	v_rcp_f32_e32 v2, v6
	v_rcp_f32_e32 v3, v7
	v_rcp_f32_e32 v24, v24
	v_rcp_f32_e32 v25, v25
	v_rcp_f32_e32 v23, v23
	v_pk_mul_f32 v[6:7], v[124:125], v[2:3] op_sel_hi:[0,1]
	v_pk_mul_f32 v[4:5], v[124:125], v[0:1] op_sel_hi:[0,1]
	v_pk_mul_f32 v[2:3], v[124:125], v[24:25] op_sel_hi:[0,1]
	v_pk_mul_f32 v[0:1], v[124:125], v[22:23] op_sel_hi:[0,1]
	s_and_b64 vcc, exec, s[24:25]
	s_cbranch_vccz .LBB0_690
	s_branch .LBB0_769

; __device__ __forceinline__ float sigmoidf_(float z) { return __builtin_amdgcn_rcpf(1.0f + __expf(-z)); }
;     __device__ __forceinline__ void operator()(const f32x4 (&acc)[2][2][4][2], const Unit& u, int wr, int wc, int fr, int fq) const {
;     ...
;                         if (grp < 4) {
;                             const int bc = col - grp * 512;
;                             const f32x4 c0 = *(const f32x4*)(bias + bc), c1 = *(const f32x4*)(bias + bc + 4);
;                             const float mul = grp < 2 ? -0.60653066f : 1.0f;
; #pragma unroll
;                             for (int j = 0; j < 4; ++j) { v0[j] = mul * sigmoidf_(v0[j] + c0[j]); v1[j] = mul * sigmoidf_(v1[j] + c1[j]); }
.LBB0_731:
	v_subrev_u32_e32 v158, s7, v146
	v_ashrrev_i32_e32 v159, 31, v158
	v_lshl_add_u64 v[158:159], v[158:159], 2, s[62:63]
	global_load_dwordx4 v[210:213], v[158:159], off
	global_load_dwordx4 v[214:217], v[158:159], off offset:16
	global_load_dwordx4 v[218:221], v[158:159], off offset:512
	global_load_dwordx4 v[222:225], v[158:159], off offset:528
	s_waitcnt vmcnt(0)
	v_mov_b32_e32 v194, v210
	v_mov_b32_e32 v195, v211
	v_mov_b32_e32 v196, v212
	v_mov_b32_e32 v197, v213
	v_mov_b32_e32 v198, v214
	v_mov_b32_e32 v199, v215
	v_mov_b32_e32 v200, v216
	v_mov_b32_e32 v201, v217
	v_add_f32_e32 v125, v128, v194
	v_add_f32_e32 v128, v150, v198
	v_add_f32_e32 v129, v129, v195
	v_add_f32_e32 v150, v151, v199
	v_add_f32_e32 v130, v130, v196
	v_add_f32_e32 v126, v126, v200
	v_add_f32_e32 v131, v131, v197
	v_add_f32_e32 v127, v127, v201
	v_mul_f32_e32 v125, 0xbfb8aa3b, v125
	v_mul_f32_e32 v128, 0xbfb8aa3b, v128
	v_mul_f32_e32 v129, 0xbfb8aa3b, v129
	v_mul_f32_e32 v150, 0xbfb8aa3b, v150
	v_mul_f32_e32 v130, 0xbfb8aa3b, v130
	v_mul_f32_e32 v126, 0xbfb8aa3b, v126
	v_mul_f32_e32 v131, 0xbfb8aa3b, v131
	v_mul_f32_e32 v127, 0xbfb8aa3b, v127
	v_exp_f32_e32 v125, v125
	v_exp_f32_e32 v128, v128
	v_exp_f32_e32 v129, v129
	v_exp_f32_e32 v150, v150
	v_exp_f32_e32 v130, v130
	v_exp_f32_e32 v126, v126
	v_exp_f32_e32 v131, v131
	v_exp_f32_e32 v127, v127
	v_add_f32_e32 v125, 1.0, v125
	v_add_f32_e32 v128, 1.0, v128
	v_add_f32_e32 v129, 1.0, v129
	v_add_f32_e32 v151, 1.0, v150
	v_add_f32_e32 v130, 1.0, v130
	v_add_f32_e32 v153, 1.0, v126
	v_add_f32_e32 v131, 1.0, v131
	v_add_f32_e32 v159, 1.0, v127
	v_rcp_f32_e32 v126, v125
	v_rcp_f32_e32 v150, v128
	v_rcp_f32_e32 v127, v129
	v_rcp_f32_e32 v128, v130
	v_rcp_f32_e32 v129, v131
	v_rcp_f32_e32 v158, v153
	v_rcp_f32_e32 v159, v159
	v_rcp_f32_e32 v151, v151
	v_pk_mul_f32 v[130:131], v[124:125], v[128:129] op_sel_hi:[0,1]
	v_pk_mul_f32 v[128:129], v[124:125], v[126:127] op_sel_hi:[0,1]
	v_pk_mul_f32 v[126:127], v[124:125], v[158:159] op_sel_hi:[0,1]
	v_pk_mul_f32 v[150:151], v[124:125], v[150:151] op_sel_hi:[0,1]

; __device__ __forceinline__ float sigmoidf_(float z) { return __builtin_amdgcn_rcpf(1.0f + __expf(-z)); }
;     __device__ __forceinline__ void operator()(const f32x4 (&acc)[2][2][4][2], const Unit& u, int wr, int wc, int fr, int fq) const {
;     ...
;                         if (grp < 4) {
;                             const int bc = col - grp * 512;
;                             const f32x4 c0 = *(const f32x4*)(bias + bc), c1 = *(const f32x4*)(bias + bc + 4);
;                             const float mul = grp < 2 ? -0.60653066f : 1.0f;
; #pragma unroll
;                             for (int j = 0; j < 4; ++j) { v0[j] = mul * sigmoidf_(v0[j] + c0[j]); v1[j] = mul * sigmoidf_(v1[j] + c1[j]); }
.LBB0_736:
	v_subrev_u32_e32 v126, s7, v146
	v_ashrrev_i32_e32 v127, 31, v126
	v_lshl_add_u64 v[126:127], v[126:127], 2, s[62:63]
	v_mov_b32_e32 v150, v210
	v_mov_b32_e32 v151, v211
	v_mov_b32_e32 v152, v212
	v_mov_b32_e32 v153, v213
	v_mov_b32_e32 v154, v214
	v_mov_b32_e32 v155, v215
	v_mov_b32_e32 v156, v216
	v_mov_b32_e32 v157, v217
	v_add_f32_e32 v112, v112, v150
	v_add_f32_e32 v108, v108, v154
	v_add_f32_e32 v113, v113, v151
	v_add_f32_e32 v109, v109, v155
	v_add_f32_e32 v114, v114, v152
	v_add_f32_e32 v110, v110, v156
	v_add_f32_e32 v115, v115, v153
	v_add_f32_e32 v111, v111, v157
	v_mul_f32_e32 v112, 0xbfb8aa3b, v112
	v_mul_f32_e32 v108, 0xbfb8aa3b, v108
	v_mul_f32_e32 v113, 0xbfb8aa3b, v113
	v_mul_f32_e32 v109, 0xbfb8aa3b, v109
	v_mul_f32_e32 v114, 0xbfb8aa3b, v114
	v_mul_f32_e32 v110, 0xbfb8aa3b, v110
	v_mul_f32_e32 v115, 0xbfb8aa3b, v115
	v_mul_f32_e32 v111, 0xbfb8aa3b, v111
	v_exp_f32_e32 v112, v112
	v_exp_f32_e32 v108, v108
	v_exp_f32_e32 v113, v113
	v_exp_f32_e32 v109, v109
	v_exp_f32_e32 v114, v114
	v_exp_f32_e32 v110, v110
	v_exp_f32_e32 v115, v115
	v_exp_f32_e32 v111, v111
	v_add_f32_e32 v112, 1.0, v112
	v_add_f32_e32 v119, 1.0, v108
	v_add_f32_e32 v113, 1.0, v113
	v_add_f32_e32 v127, 1.0, v109
	v_add_f32_e32 v114, 1.0, v114
	v_add_f32_e32 v129, 1.0, v110
	v_add_f32_e32 v115, 1.0, v115
	v_add_f32_e32 v131, 1.0, v111
	v_rcp_f32_e32 v108, v112
	v_rcp_f32_e32 v126, v119
	v_rcp_f32_e32 v109, v113
	v_rcp_f32_e32 v110, v114
	v_rcp_f32_e32 v111, v115
	v_rcp_f32_e32 v130, v129
	v_rcp_f32_e32 v131, v131
	v_rcp_f32_e32 v127, v127
	v_pk_mul_f32 v[114:115], v[124:125], v[110:111] op_sel_hi:[0,1]
	v_pk_mul_f32 v[112:113], v[124:125], v[108:109] op_sel_hi:[0,1]
	v_pk_mul_f32 v[110:111], v[124:125], v[130:131] op_sel_hi:[0,1]
	v_pk_mul_f32 v[108:109], v[124:125], v[126:127] op_sel_hi:[0,1]

; __device__ __forceinline__ float sigmoidf_(float z) { return __builtin_amdgcn_rcpf(1.0f + __expf(-z)); }
;     __device__ __forceinline__ void operator()(const f32x4 (&acc)[2][2][4][2], const Unit& u, int wr, int wc, int fr, int fq) const {
;     ...
;                         if (grp < 4) {
;                             const int bc = col - grp * 512;
;                             const f32x4 c0 = *(const f32x4*)(bias + bc), c1 = *(const f32x4*)(bias + bc + 4);
;                             const float mul = grp < 2 ? -0.60653066f : 1.0f;
; #pragma unroll
;                             for (int j = 0; j < 4; ++j) { v0[j] = mul * sigmoidf_(v0[j] + c0[j]); v1[j] = mul * sigmoidf_(v1[j] + c1[j]); }
.LBB0_739:
	v_subrev_u32_e32 v106, s7, v146
	v_ashrrev_i32_e32 v107, 31, v106
	v_lshl_add_u64 v[110:111], v[106:107], 2, s[62:63]
	v_mov_b32_e32 v106, v210
	v_mov_b32_e32 v107, v211
	v_mov_b32_e32 v108, v212
	v_mov_b32_e32 v109, v213
	v_mov_b32_e32 v110, v214
	v_mov_b32_e32 v111, v215
	v_mov_b32_e32 v112, v216
	v_mov_b32_e32 v113, v217
	v_add_f32_e32 v96, v96, v106
	v_add_f32_e32 v92, v92, v110
	v_add_f32_e32 v97, v97, v107
	v_add_f32_e32 v93, v93, v111
	v_add_f32_e32 v98, v98, v108
	v_add_f32_e32 v94, v94, v112
	v_add_f32_e32 v99, v99, v109
	v_add_f32_e32 v95, v95, v113
	v_mul_f32_e32 v96, 0xbfb8aa3b, v96
	v_mul_f32_e32 v92, 0xbfb8aa3b, v92
	v_mul_f32_e32 v97, 0xbfb8aa3b, v97
	v_mul_f32_e32 v93, 0xbfb8aa3b, v93
	v_mul_f32_e32 v98, 0xbfb8aa3b, v98
	v_mul_f32_e32 v94, 0xbfb8aa3b, v94
	v_mul_f32_e32 v99, 0xbfb8aa3b, v99
	v_mul_f32_e32 v95, 0xbfb8aa3b, v95
	v_exp_f32_e32 v96, v96
	v_exp_f32_e32 v92, v92
	v_exp_f32_e32 v97, v97
	v_exp_f32_e32 v93, v93
	v_exp_f32_e32 v98, v98
	v_exp_f32_e32 v94, v94
	v_exp_f32_e32 v99, v99
	v_exp_f32_e32 v95, v95
	v_add_f32_e32 v96, 1.0, v96
	v_add_f32_e32 v101, 1.0, v92
	v_add_f32_e32 v97, 1.0, v97
	v_add_f32_e32 v107, 1.0, v93
	v_add_f32_e32 v98, 1.0, v98
	v_add_f32_e32 v108, 1.0, v94
	v_add_f32_e32 v99, 1.0, v99
	v_add_f32_e32 v109, 1.0, v95
	v_rcp_f32_e32 v92, v96
	v_rcp_f32_e32 v106, v101
	v_rcp_f32_e32 v93, v97
	v_rcp_f32_e32 v94, v98
	v_rcp_f32_e32 v95, v99
	v_rcp_f32_e32 v108, v108
	v_rcp_f32_e32 v109, v109
	v_rcp_f32_e32 v107, v107
	v_pk_mul_f32 v[98:99], v[124:125], v[94:95] op_sel_hi:[0,1]
	v_pk_mul_f32 v[96:97], v[124:125], v[92:93] op_sel_hi:[0,1]
	v_pk_mul_f32 v[94:95], v[124:125], v[108:109] op_sel_hi:[0,1]
	v_pk_mul_f32 v[92:93], v[124:125], v[106:107] op_sel_hi:[0,1]

; __device__ __forceinline__ float sigmoidf_(float z) { return __builtin_amdgcn_rcpf(1.0f + __expf(-z)); }
;     __device__ __forceinline__ void operator()(const f32x4 (&acc)[2][2][4][2], const Unit& u, int wr, int wc, int fr, int fq) const {
;     ...
;                         if (grp < 4) {
;                             const int bc = col - grp * 512;
;                             const f32x4 c0 = *(const f32x4*)(bias + bc), c1 = *(const f32x4*)(bias + bc + 4);
;                             const float mul = grp < 2 ? -0.60653066f : 1.0f;
; #pragma unroll
;                             for (int j = 0; j < 4; ++j) { v0[j] = mul * sigmoidf_(v0[j] + c0[j]); v1[j] = mul * sigmoidf_(v1[j] + c1[j]); }
.LBB0_742:
	v_subrev_u32_e32 v90, s7, v146
	v_ashrrev_i32_e32 v91, 31, v90
	v_lshl_add_u64 v[94:95], v[90:91], 2, s[62:63]
	v_mov_b32_e32 v90, v210
	v_mov_b32_e32 v91, v211
	v_mov_b32_e32 v92, v212
	v_mov_b32_e32 v93, v213
	v_mov_b32_e32 v94, v214
	v_mov_b32_e32 v95, v215
	v_mov_b32_e32 v96, v216
	v_mov_b32_e32 v97, v217
	v_add_f32_e32 v80, v80, v90
	v_add_f32_e32 v76, v76, v94
	v_add_f32_e32 v81, v81, v91
	v_add_f32_e32 v77, v77, v95
	v_add_f32_e32 v82, v82, v92
	v_add_f32_e32 v78, v78, v96
	v_add_f32_e32 v83, v83, v93
	v_add_f32_e32 v79, v79, v97
	v_mul_f32_e32 v80, 0xbfb8aa3b, v80
	v_mul_f32_e32 v76, 0xbfb8aa3b, v76
	v_mul_f32_e32 v81, 0xbfb8aa3b, v81
	v_mul_f32_e32 v77, 0xbfb8aa3b, v77
	v_mul_f32_e32 v82, 0xbfb8aa3b, v82
	v_mul_f32_e32 v78, 0xbfb8aa3b, v78
	v_mul_f32_e32 v83, 0xbfb8aa3b, v83
	v_mul_f32_e32 v79, 0xbfb8aa3b, v79
	v_exp_f32_e32 v80, v80
	v_exp_f32_e32 v76, v76
	v_exp_f32_e32 v81, v81
	v_exp_f32_e32 v77, v77
	v_exp_f32_e32 v82, v82
	v_exp_f32_e32 v78, v78
	v_exp_f32_e32 v83, v83
	v_exp_f32_e32 v79, v79
	v_add_f32_e32 v80, 1.0, v80
	v_add_f32_e32 v85, 1.0, v76
	v_add_f32_e32 v81, 1.0, v81
	v_add_f32_e32 v91, 1.0, v77
	v_add_f32_e32 v82, 1.0, v82
	v_add_f32_e32 v92, 1.0, v78
	v_add_f32_e32 v83, 1.0, v83
	v_add_f32_e32 v93, 1.0, v79
	v_rcp_f32_e32 v76, v80
	v_rcp_f32_e32 v90, v85
	v_rcp_f32_e32 v77, v81
	v_rcp_f32_e32 v78, v82
	v_rcp_f32_e32 v79, v83
	v_rcp_f32_e32 v92, v92
	v_rcp_f32_e32 v93, v93
	v_rcp_f32_e32 v91, v91
	v_pk_mul_f32 v[82:83], v[124:125], v[78:79] op_sel_hi:[0,1]
	v_pk_mul_f32 v[80:81], v[124:125], v[76:77] op_sel_hi:[0,1]
	v_pk_mul_f32 v[78:79], v[124:125], v[92:93] op_sel_hi:[0,1]
	v_pk_mul_f32 v[76:77], v[124:125], v[90:91] op_sel_hi:[0,1]

; __device__ __forceinline__ float sigmoidf_(float z) { return __builtin_amdgcn_rcpf(1.0f + __expf(-z)); }
;     __device__ __forceinline__ void operator()(const f32x4 (&acc)[2][2][4][2], const Unit& u, int wr, int wc, int fr, int fq) const {
;     ...
;                         if (grp < 4) {
;                             const int bc = col - grp * 512;
;                             const f32x4 c0 = *(const f32x4*)(bias + bc), c1 = *(const f32x4*)(bias + bc + 4);
;                             const float mul = grp < 2 ? -0.60653066f : 1.0f;
; #pragma unroll
;                             for (int j = 0; j < 4; ++j) { v0[j] = mul * sigmoidf_(v0[j] + c0[j]); v1[j] = mul * sigmoidf_(v1[j] + c1[j]); }
.LBB0_745:
	v_subrev_u32_e32 v74, s7, v146
	v_ashrrev_i32_e32 v75, 31, v74
	v_lshl_add_u64 v[78:79], v[74:75], 2, s[62:63]
	v_mov_b32_e32 v74, v210
	v_mov_b32_e32 v75, v211
	v_mov_b32_e32 v76, v212
	v_mov_b32_e32 v77, v213
	v_mov_b32_e32 v78, v214
	v_mov_b32_e32 v79, v215
	v_mov_b32_e32 v80, v216
	v_mov_b32_e32 v81, v217
	v_add_f32_e32 v64, v64, v74
	v_add_f32_e32 v60, v60, v78
	v_add_f32_e32 v65, v65, v75
	v_add_f32_e32 v61, v61, v79
	v_add_f32_e32 v66, v66, v76
	v_add_f32_e32 v62, v62, v80
	v_add_f32_e32 v67, v67, v77
	v_add_f32_e32 v63, v63, v81
	v_mul_f32_e32 v64, 0xbfb8aa3b, v64
	v_mul_f32_e32 v60, 0xbfb8aa3b, v60
	v_mul_f32_e32 v65, 0xbfb8aa3b, v65
	v_mul_f32_e32 v61, 0xbfb8aa3b, v61
	v_mul_f32_e32 v66, 0xbfb8aa3b, v66
	v_mul_f32_e32 v62, 0xbfb8aa3b, v62
	v_mul_f32_e32 v67, 0xbfb8aa3b, v67
	v_mul_f32_e32 v63, 0xbfb8aa3b, v63
	v_exp_f32_e32 v64, v64
	v_exp_f32_e32 v60, v60
	v_exp_f32_e32 v65, v65
	v_exp_f32_e32 v61, v61
	v_exp_f32_e32 v66, v66
	v_exp_f32_e32 v62, v62
	v_exp_f32_e32 v67, v67
	v_exp_f32_e32 v63, v63
	v_add_f32_e32 v64, 1.0, v64
	v_add_f32_e32 v69, 1.0, v60
	v_add_f32_e32 v65, 1.0, v65
	v_add_f32_e32 v75, 1.0, v61
	v_add_f32_e32 v66, 1.0, v66
	v_add_f32_e32 v76, 1.0, v62
	v_add_f32_e32 v67, 1.0, v67
	v_add_f32_e32 v77, 1.0, v63
	v_rcp_f32_e32 v60, v64
	v_rcp_f32_e32 v74, v69
	v_rcp_f32_e32 v61, v65
	v_rcp_f32_e32 v62, v66
	v_rcp_f32_e32 v63, v67
	v_rcp_f32_e32 v76, v76
	v_rcp_f32_e32 v77, v77
	v_rcp_f32_e32 v75, v75
	v_pk_mul_f32 v[66:67], v[124:125], v[62:63] op_sel_hi:[0,1]
	v_pk_mul_f32 v[64:65], v[124:125], v[60:61] op_sel_hi:[0,1]
	v_pk_mul_f32 v[62:63], v[124:125], v[76:77] op_sel_hi:[0,1]
	v_pk_mul_f32 v[60:61], v[124:125], v[74:75] op_sel_hi:[0,1]

; __device__ __forceinline__ float sigmoidf_(float z) { return __builtin_amdgcn_rcpf(1.0f + __expf(-z)); }
;     __device__ __forceinline__ void operator()(const f32x4 (&acc)[2][2][4][2], const Unit& u, int wr, int wc, int fr, int fq) const {
;     ...
;                         if (grp < 4) {
;                             const int bc = col - grp * 512;
;                             const f32x4 c0 = *(const f32x4*)(bias + bc), c1 = *(const f32x4*)(bias + bc + 4);
;                             const float mul = grp < 2 ? -0.60653066f : 1.0f;
; #pragma unroll
;                             for (int j = 0; j < 4; ++j) { v0[j] = mul * sigmoidf_(v0[j] + c0[j]); v1[j] = mul * sigmoidf_(v1[j] + c1[j]); }
.LBB0_748:
	v_subrev_u32_e32 v58, s7, v146
	v_ashrrev_i32_e32 v59, 31, v58
	v_lshl_add_u64 v[62:63], v[58:59], 2, s[62:63]
	v_mov_b32_e32 v58, v210
	v_mov_b32_e32 v59, v211
	v_mov_b32_e32 v60, v212
	v_mov_b32_e32 v61, v213
	v_mov_b32_e32 v62, v214
	v_mov_b32_e32 v63, v215
	v_mov_b32_e32 v64, v216
	v_mov_b32_e32 v65, v217
	v_add_f32_e32 v48, v48, v58
	v_add_f32_e32 v44, v44, v62
	v_add_f32_e32 v49, v49, v59
	v_add_f32_e32 v45, v45, v63
	v_add_f32_e32 v50, v50, v60
	v_add_f32_e32 v46, v46, v64
	v_add_f32_e32 v51, v51, v61
	v_add_f32_e32 v47, v47, v65
	v_mul_f32_e32 v48, 0xbfb8aa3b, v48
	v_mul_f32_e32 v44, 0xbfb8aa3b, v44
	v_mul_f32_e32 v49, 0xbfb8aa3b, v49
	v_mul_f32_e32 v45, 0xbfb8aa3b, v45
	v_mul_f32_e32 v50, 0xbfb8aa3b, v50
	v_mul_f32_e32 v46, 0xbfb8aa3b, v46
	v_mul_f32_e32 v51, 0xbfb8aa3b, v51
	v_mul_f32_e32 v47, 0xbfb8aa3b, v47
	v_exp_f32_e32 v48, v48
	v_exp_f32_e32 v44, v44
	v_exp_f32_e32 v49, v49
	v_exp_f32_e32 v45, v45
	v_exp_f32_e32 v50, v50
	v_exp_f32_e32 v46, v46
	v_exp_f32_e32 v51, v51
	v_exp_f32_e32 v47, v47
	v_add_f32_e32 v48, 1.0, v48
	v_add_f32_e32 v53, 1.0, v44
	v_add_f32_e32 v49, 1.0, v49
	v_add_f32_e32 v59, 1.0, v45
	v_add_f32_e32 v50, 1.0, v50
	v_add_f32_e32 v60, 1.0, v46
	v_add_f32_e32 v51, 1.0, v51
	v_add_f32_e32 v61, 1.0, v47
	v_rcp_f32_e32 v44, v48
	v_rcp_f32_e32 v58, v53
	v_rcp_f32_e32 v45, v49
	v_rcp_f32_e32 v46, v50
	v_rcp_f32_e32 v47, v51
	v_rcp_f32_e32 v60, v60
	v_rcp_f32_e32 v61, v61
	v_rcp_f32_e32 v59, v59
	v_pk_mul_f32 v[50:51], v[124:125], v[46:47] op_sel_hi:[0,1]
	v_pk_mul_f32 v[48:49], v[124:125], v[44:45] op_sel_hi:[0,1]
	v_pk_mul_f32 v[46:47], v[124:125], v[60:61] op_sel_hi:[0,1]
	v_pk_mul_f32 v[44:45], v[124:125], v[58:59] op_sel_hi:[0,1]

; __device__ __forceinline__ float sigmoidf_(float z) { return __builtin_amdgcn_rcpf(1.0f + __expf(-z)); }
;     __device__ __forceinline__ void operator()(const f32x4 (&acc)[2][2][4][2], const Unit& u, int wr, int wc, int fr, int fq) const {
;     ...
;                         if (grp < 4) {
;                             const int bc = col - grp * 512;
;                             const f32x4 c0 = *(const f32x4*)(bias + bc), c1 = *(const f32x4*)(bias + bc + 4);
;                             const float mul = grp < 2 ? -0.60653066f : 1.0f;
; #pragma unroll
;                             for (int j = 0; j < 4; ++j) { v0[j] = mul * sigmoidf_(v0[j] + c0[j]); v1[j] = mul * sigmoidf_(v1[j] + c1[j]); }
.LBB0_751:
	v_subrev_u32_e32 v42, s7, v146
	v_ashrrev_i32_e32 v43, 31, v42
	v_lshl_add_u64 v[46:47], v[42:43], 2, s[62:63]
	v_mov_b32_e32 v42, v210
	v_mov_b32_e32 v43, v211
	v_mov_b32_e32 v44, v212
	v_mov_b32_e32 v45, v213
	v_mov_b32_e32 v46, v214
	v_mov_b32_e32 v47, v215
	v_mov_b32_e32 v48, v216
	v_mov_b32_e32 v49, v217
	v_add_f32_e32 v32, v32, v42
	v_add_f32_e32 v28, v28, v46
	v_add_f32_e32 v33, v33, v43
	v_add_f32_e32 v29, v29, v47
	v_add_f32_e32 v34, v34, v44
	v_add_f32_e32 v30, v30, v48
	v_add_f32_e32 v35, v35, v45
	v_add_f32_e32 v31, v31, v49
	v_mul_f32_e32 v32, 0xbfb8aa3b, v32
	v_mul_f32_e32 v28, 0xbfb8aa3b, v28
	v_mul_f32_e32 v33, 0xbfb8aa3b, v33
	v_mul_f32_e32 v29, 0xbfb8aa3b, v29
	v_mul_f32_e32 v34, 0xbfb8aa3b, v34
	v_mul_f32_e32 v30, 0xbfb8aa3b, v30
	v_mul_f32_e32 v35, 0xbfb8aa3b, v35
	v_mul_f32_e32 v31, 0xbfb8aa3b, v31
	v_exp_f32_e32 v32, v32
	v_exp_f32_e32 v28, v28
	v_exp_f32_e32 v33, v33
	v_exp_f32_e32 v29, v29
	v_exp_f32_e32 v34, v34
	v_exp_f32_e32 v30, v30
	v_exp_f32_e32 v35, v35
	v_exp_f32_e32 v31, v31
	v_add_f32_e32 v32, 1.0, v32
	v_add_f32_e32 v37, 1.0, v28
	v_add_f32_e32 v33, 1.0, v33
	v_add_f32_e32 v43, 1.0, v29
	v_add_f32_e32 v34, 1.0, v34
	v_add_f32_e32 v44, 1.0, v30
	v_add_f32_e32 v35, 1.0, v35
	v_add_f32_e32 v45, 1.0, v31
	v_rcp_f32_e32 v28, v32
	v_rcp_f32_e32 v42, v37
	v_rcp_f32_e32 v29, v33
	v_rcp_f32_e32 v30, v34
	v_rcp_f32_e32 v31, v35
	v_rcp_f32_e32 v44, v44
	v_rcp_f32_e32 v45, v45
	v_rcp_f32_e32 v43, v43
	v_pk_mul_f32 v[34:35], v[124:125], v[30:31] op_sel_hi:[0,1]
	v_pk_mul_f32 v[32:33], v[124:125], v[28:29] op_sel_hi:[0,1]
	v_pk_mul_f32 v[30:31], v[124:125], v[44:45] op_sel_hi:[0,1]
	v_pk_mul_f32 v[28:29], v[124:125], v[42:43] op_sel_hi:[0,1]

; __device__ __forceinline__ float sigmoidf_(float z) { return __builtin_amdgcn_rcpf(1.0f + __expf(-z)); }
;     __device__ __forceinline__ void operator()(const f32x4 (&acc)[2][2][4][2], const Unit& u, int wr, int wc, int fr, int fq) const {
;     ...
;                         if (grp < 4) {
;                             const int bc = col - grp * 512;
;                             const f32x4 c0 = *(const f32x4*)(bias + bc), c1 = *(const f32x4*)(bias + bc + 4);
;                             const float mul = grp < 2 ? -0.60653066f : 1.0f;
; #pragma unroll
;                             for (int j = 0; j < 4; ++j) { v0[j] = mul * sigmoidf_(v0[j] + c0[j]); v1[j] = mul * sigmoidf_(v1[j] + c1[j]); }
.LBB0_754:
	v_subrev_u32_e32 v26, s7, v146
	v_ashrrev_i32_e32 v27, 31, v26
	v_lshl_add_u64 v[30:31], v[26:27], 2, s[62:63]
	v_mov_b32_e32 v26, v210
	v_mov_b32_e32 v27, v211
	v_mov_b32_e32 v28, v212
	v_mov_b32_e32 v29, v213
	v_mov_b32_e32 v30, v214
	v_mov_b32_e32 v31, v215
	v_mov_b32_e32 v32, v216
	v_mov_b32_e32 v33, v217
	v_add_f32_e32 v12, v12, v26
	v_add_f32_e32 v8, v8, v30
	v_add_f32_e32 v13, v13, v27
	v_add_f32_e32 v9, v9, v31
	v_add_f32_e32 v14, v14, v28
	v_add_f32_e32 v10, v10, v32
	v_add_f32_e32 v15, v15, v29
	v_add_f32_e32 v11, v11, v33
	v_mul_f32_e32 v12, 0xbfb8aa3b, v12
	v_mul_f32_e32 v8, 0xbfb8aa3b, v8
	v_mul_f32_e32 v13, 0xbfb8aa3b, v13
	v_mul_f32_e32 v9, 0xbfb8aa3b, v9
	v_mul_f32_e32 v14, 0xbfb8aa3b, v14
	v_mul_f32_e32 v10, 0xbfb8aa3b, v10
	v_mul_f32_e32 v15, 0xbfb8aa3b, v15
	v_mul_f32_e32 v11, 0xbfb8aa3b, v11
	v_exp_f32_e32 v12, v12
	v_exp_f32_e32 v8, v8
	v_exp_f32_e32 v13, v13
	v_exp_f32_e32 v9, v9
	v_exp_f32_e32 v14, v14
	v_exp_f32_e32 v10, v10
	v_exp_f32_e32 v15, v15
	v_exp_f32_e32 v11, v11
	v_add_f32_e32 v12, 1.0, v12
	v_add_f32_e32 v21, 1.0, v8
	v_add_f32_e32 v13, 1.0, v13
	v_add_f32_e32 v27, 1.0, v9
	v_add_f32_e32 v14, 1.0, v14
	v_add_f32_e32 v28, 1.0, v10
	v_add_f32_e32 v15, 1.0, v15
	v_add_f32_e32 v29, 1.0, v11
	v_rcp_f32_e32 v8, v12
	v_rcp_f32_e32 v26, v21
	v_rcp_f32_e32 v9, v13
	v_rcp_f32_e32 v10, v14
	v_rcp_f32_e32 v11, v15
	v_rcp_f32_e32 v28, v28
	v_rcp_f32_e32 v29, v29
	v_rcp_f32_e32 v27, v27
	v_pk_mul_f32 v[14:15], v[124:125], v[10:11] op_sel_hi:[0,1]
	v_pk_mul_f32 v[12:13], v[124:125], v[8:9] op_sel_hi:[0,1]
	v_pk_mul_f32 v[10:11], v[124:125], v[28:29] op_sel_hi:[0,1]
	v_pk_mul_f32 v[8:9], v[124:125], v[26:27] op_sel_hi:[0,1]
